# GLU GEMM epilogue: yd/d_z loads pipelined 3 row groups deep with counted waits; dilated-attention work ticket fetched one item ahead
# speedup vs baseline: 1.0035x; 1.0035x over previous
; #define LAS __attribute__((address_space(3)))
; __global__ void __launch_bounds__(512, 2) fwd_mega(Params Pk) {
;     ...
;           unsigned* ticket = (unsigned*)(P->ws + W_BAR + 14336) + l * 64;
;           volatile LAS int* tk = (volatile LAS int*)(lds + LDS_BYTES - 32);
;           for (;;) {
;               if (threadIdx.x == 0) tk[0] = (int)atomicAdd(ticket, 1u);
;               __syncthreads();
;               const int it = tk[0];
;               __syncthreads();
;               if (it >= 768) break;
;               const int hh = it >> 6, nq = it & 63, g = hh >> 2, dsh = 2 * g, L = SEQ >> dsh, p0 = nq * 128, n_in = (p0 & (L - 1)) >> 7;
;               const int kt_hi = p0 / 64 + 2, kt_lo = n_in == 0 ? p0 / 64 : p0 / 64 - 2;
;               const float slope = exp2f(-8.f * (float)(hh + 1) / 12.f) * (float)(1 << dsh) * 1.4426950408889634f;
;               attn_block<128>(lds, (const bf16_t*)(P->ws + W_QA) + ((size_t)hh * SEQ + p0) * 128, (const bf16_t*)(P->ws + W_KA) + (size_t)hh * SEQ * 128,
;                               (const bf16_t*)(P->ws + W_VAT) + (size_t)hh * 128 * SEQ, p0, kt_lo, kt_hi, 128, slope, dsh,
;                               (bf16_t*)(P->ws + W_OA) + (size_t)g * SEQ * 512, (float*)(P->ws + W_LSEA) + (size_t)g * SEQ * 4, hh & 3);
.LBB0_985:
	s_waitcnt vmcnt(0) lgkmcnt(0)
	s_barrier
	s_load_dwordx2 s[6:7], s[44:45], 0xf0
	v_readlane_b32 s0, v255, 46
	v_readlane_b32 s1, v255, 47
	s_lshl_b32 s38, s0, 6
	s_lshl_b64 s[0:1], s[38:39], 2
	s_waitcnt lgkmcnt(0)
	s_add_u32 s0, s6, s0
	s_addc_u32 s1, s7, s1
	s_add_u32 s0, s0, 0x3dbe5000
	s_addc_u32 s1, s1, 0
	s_add_u32 s38, s6, 0x28f00000
	s_addc_u32 s46, s7, 0
	s_add_u32 s47, s6, 0x2a700000
	s_addc_u32 s48, s7, 0
	s_add_u32 s49, s6, 0x2bf00000
	s_addc_u32 s50, s7, 0
	s_add_u32 s51, s6, 0x31f00000
	s_addc_u32 s52, s7, 0
	s_add_u32 s53, s6, 0x34f00000
	s_addc_u32 s54, s7, 0
	s_add_u32 s55, s6, 0x2bf00080
	s_addc_u32 s81, s7, 0
	s_add_u32 s6, s6, 0x2a704000
	s_addc_u32 s7, s7, 0
	s_and_saveexec_b64 s[20:21], s[96:97]
	s_cbranch_execz .Lmy_tk_first
	v_mov_b32_e32 v241, 1
	global_atomic_add v240, v1, v241, s[0:1] sc0
.Lmy_tk_first:
	s_or_b64 exec, exec, s[20:21]
	s_branch .LBB0_988
.LBB0_986:
	s_or_b64 exec, exec, s[20:21]
	s_mov_b64 s[20:21], 0

; __global__ void __launch_bounds__(512, 2) fwd_mega(Params Pk) {
;     ...
;           for (;;) {
;               if (threadIdx.x == 0) tk[0] = (int)atomicAdd(ticket, 1u);
;               __syncthreads();
;               const int it = tk[0];
;               __syncthreads();
;               if (it >= 768) break;
.LBB0_988:
	s_and_saveexec_b64 s[20:21], s[96:97]
	s_cbranch_execz .LBB0_992
	s_waitcnt vmcnt(0)
	v_readlane_b32 s4, v255, 31
	v_mov_b32_e32 v0, v240
	s_nop 1
	v_mov_b32_e32 v2, s4
	ds_write_b32 v2, v0
	v_mov_b32_e32 v241, 1
	global_atomic_add v240, v1, v241, s[0:1] sc0

; #define PG8_STAGE(bufoff, gbase) PG8_STAGE_(bufoff, gbase, voffA)
; #define PG8_STAGEB(bufoff, gbase) PG8_STAGE_(bufoff, gbase, voffB)
; #define PG8_LDA(dst, b, h) do { _Pragma("unroll") for (int m = 0; m < 4; ++m) _Pragma("unroll") for (int k = 0; k < 2; ++k) dst[m][k] = *(const LAS bf16x8*)(lds + PG8_SA(b, h) + aoff + m * 2048 + k * 1024); } while (0)
; #define PG8_LDB(dst, b, h) do { _Pragma("unroll") for (int n = 0; n < 2; ++n) _Pragma("unroll") for (int k = 0; k < 2; ++k) dst[n][k] = *(const LAS bf16x8*)(lds + PG8_SB(b, h) + boff + n * 2048 + k * 1024); } while (0)
; #define PG8_MMA(ai, bj, At, Bt) do { __builtin_amdgcn_s_setprio(1); _Pragma("unroll") for (int m = 0; m < 4; ++m) _Pragma("unroll") for (int n = 0; n < 2; ++n) _Pragma("unroll") for (int k = 0; k < 2; ++k) \
;         acc[ai][bj][m][n] = __builtin_amdgcn_mfma_f32_16x16x32_bf16(Bt[n][k], At[m][k], acc[ai][bj][m][n], 0, 0, 0); __builtin_amdgcn_s_setprio(0); } while (0)
; #define PG8_WAIT_V(n) asm volatile("s_waitcnt vmcnt(" #n ")" ::: "memory")
; template <class Epi>
; __device__ __forceinline__ void gemm_phase(LAS unsigned char* lds, const Gemm g, const StaticOrder& S, const Epi& E) {
;     ...
;             PG8_LDB(B0, 0, 0); PG8_SCHED; PG8_LDA(At, 0, 0); PG8_STAGE(PG8_SA(1, 1), a1 + hstep);
;             PG8_WAIT_L(8); PG8_BAR; PG8_WAIT_L(0); PG8_MMA(0, 0, At, B0); PG8_BAR; PG8_SCHED;
;             PG8_LDB(B1, 0, 1); PG8_STAGEB(PG8_SB(0, 0), b2);
;             PG8_BAR; PG8_WAIT_L(0); PG8_MMA(0, 1, At, B1); PG8_BAR;
;             PG8_LDA(At, 0, 1); PG8_STAGE(PG8_SA(0, 0), a2);
;             PG8_BAR; PG8_WAIT_L(0); PG8_MMA(1, 0, At, B0); PG8_BAR; PG8_SCHED;
;             PG8_STAGEB(PG8_SB(0, 1), b2 + hstep);
;             PG8_WAIT_V(6); PG8_BAR; PG8_MMA(1, 1, At, B1); PG8_BAR;
;             PG8_LDB(B0, 1, 0); PG8_SCHED; PG8_LDA(At, 1, 0); PG8_STAGE(PG8_SA(0, 1), a2 + hstep);
;             PG8_WAIT_L(8); PG8_BAR; PG8_WAIT_L(0); PG8_MMA(0, 0, At, B0); PG8_BAR; PG8_SCHED;
;             PG8_LDB(B1, 1, 1); PG8_STAGEB(PG8_SB(1, 0), b3);
;             PG8_BAR; PG8_WAIT_L(0); PG8_MMA(0, 1, At, B1); PG8_BAR;
;             PG8_LDA(At, 1, 1); PG8_STAGE(PG8_SA(1, 0), a3);
;             PG8_BAR; PG8_WAIT_L(0); PG8_MMA(1, 0, At, B0); PG8_BAR; PG8_SCHED;
;             PG8_STAGEB(PG8_SB(1, 1), b3 + hstep);
;             PG8_WAIT_V(6); PG8_BAR; PG8_MMA(1, 1, At, B1); PG8_BAR;
.LBB0_1302:
	s_add_u32 s20, s6, 0xfffe0080
	s_addc_u32 s21, s7, -1
	s_add_i32 s58, 0, 0x10000
	v_add_u32_e32 v142, s58, v206
	ds_read_b128 v[130:133], v142
	ds_read_b128 v[134:137], v142 offset:1024
	ds_read_b128 v[138:141], v142 offset:2048
	ds_read_b128 v[142:145], v142 offset:3072
	s_cmp_eq_u32 s89, 4
	s_cselect_b32 s25, s30, s21
	s_cselect_b32 s24, s31, s20
	s_cselect_b32 s21, s53, s88
	s_cselect_b32 s20, s55, s87
	v_lshl_add_u64 v[154:155], s[6:7], 0, v[162:163]
	s_add_i32 m0, s43, 0xc000
	ds_read_b128 v[146:149], v207
	ds_read_b128 v[150:153], v207 offset:1024
	ds_read_b128 v[166:169], v207 offset:2048
	ds_read_b128 v[170:173], v207 offset:3072
	ds_read_b128 v[174:177], v207 offset:4096
	ds_read_b128 v[188:191], v207 offset:5120
	ds_read_b128 v[192:195], v207 offset:6144
	ds_read_b128 v[196:199], v207 offset:7168
	global_load_lds_dwordx4 v[154:155], off
	v_lshl_add_u64 v[154:155], s[6:7], 0, v[164:165]
	s_add_i32 m0, s43, 0xe000
	s_nop 0
	global_load_lds_dwordx4 v[154:155], off
	s_waitcnt lgkmcnt(8)
	s_barrier
	s_waitcnt lgkmcnt(0)
	s_setprio 1
	v_mfma_f32_16x16x32_bf16 v[126:129], v[130:133], v[146:149], v[126:129]
	v_mfma_f32_16x16x32_bf16 v[122:125], v[138:141], v[146:149], v[122:125]
	v_mfma_f32_16x16x32_bf16 v[110:113], v[130:133], v[166:169], v[110:113]
	v_mfma_f32_16x16x32_bf16 v[106:109], v[138:141], v[166:169], v[106:109]
	v_mfma_f32_16x16x32_bf16 v[94:97], v[130:133], v[174:177], v[94:97]
	v_mfma_f32_16x16x32_bf16 v[90:93], v[138:141], v[174:177], v[90:93]
	v_mfma_f32_16x16x32_bf16 v[78:81], v[130:133], v[192:195], v[78:81]
	v_mfma_f32_16x16x32_bf16 v[74:77], v[138:141], v[192:195], v[74:77]
	v_mfma_f32_16x16x32_bf16 v[126:129], v[134:137], v[150:153], v[126:129]
	v_mfma_f32_16x16x32_bf16 v[122:125], v[142:145], v[150:153], v[122:125]
	v_mfma_f32_16x16x32_bf16 v[110:113], v[134:137], v[170:173], v[110:113]
	v_mfma_f32_16x16x32_bf16 v[106:109], v[142:145], v[170:173], v[106:109]
	v_mfma_f32_16x16x32_bf16 v[94:97], v[134:137], v[188:191], v[94:97]
	v_mfma_f32_16x16x32_bf16 v[90:93], v[142:145], v[188:191], v[90:93]
	v_mfma_f32_16x16x32_bf16 v[78:81], v[134:137], v[196:199], v[78:81]
	v_mfma_f32_16x16x32_bf16 v[74:77], v[142:145], v[196:199], v[74:77]
	s_setprio 0
	s_barrier
	s_add_i32 s90, 0, 0x14000
	v_add_u32_e32 v154, s90, v206
	s_add_i32 s58, s58, s42
	ds_read_b128 v[200:203], v154
	ds_read_b128 v[208:211], v154 offset:1024
	ds_read_b128 v[212:215], v154 offset:2048
	ds_read_b128 v[216:219], v154 offset:3072
	v_lshl_add_u64 v[154:155], s[20:21], 0, v[0:1]
	s_mov_b32 m0, s58
	v_lshl_add_u64 v[178:179], s[20:21], 0, v[156:157]
	global_load_lds_dwordx4 v[154:155], off
	s_add_i32 m0, s58, 0x2000
	s_nop 0
	global_load_lds_dwordx4 v[178:179], off
	s_barrier
	s_waitcnt lgkmcnt(0)
	s_setprio 1
	v_mfma_f32_16x16x32_bf16 v[118:121], v[200:203], v[146:149], v[118:121]
	v_mfma_f32_16x16x32_bf16 v[114:117], v[212:215], v[146:149], v[114:117]
	v_mfma_f32_16x16x32_bf16 v[102:105], v[200:203], v[166:169], v[102:105]
	v_mfma_f32_16x16x32_bf16 v[98:101], v[212:215], v[166:169], v[98:101]
	v_mfma_f32_16x16x32_bf16 v[86:89], v[200:203], v[174:177], v[86:89]
	v_mfma_f32_16x16x32_bf16 v[82:85], v[212:215], v[174:177], v[82:85]
	v_mfma_f32_16x16x32_bf16 v[70:73], v[200:203], v[192:195], v[70:73]
	v_mfma_f32_16x16x32_bf16 v[66:69], v[212:215], v[192:195], v[66:69]
	v_mfma_f32_16x16x32_bf16 v[118:121], v[208:211], v[150:153], v[118:121]
	v_mfma_f32_16x16x32_bf16 v[114:117], v[216:219], v[150:153], v[114:117]
	v_mfma_f32_16x16x32_bf16 v[102:105], v[208:211], v[170:173], v[102:105]
	v_mfma_f32_16x16x32_bf16 v[98:101], v[216:219], v[170:173], v[98:101]
	v_mfma_f32_16x16x32_bf16 v[86:89], v[208:211], v[188:191], v[86:89]
	v_mfma_f32_16x16x32_bf16 v[82:85], v[216:219], v[188:191], v[82:85]
	v_mfma_f32_16x16x32_bf16 v[70:73], v[208:211], v[196:199], v[70:73]
	v_mfma_f32_16x16x32_bf16 v[66:69], v[216:219], v[196:199], v[66:69]
	s_setprio 0
	s_mov_b32 m0, s43
	v_lshl_add_u64 v[182:183], s[24:25], 0, v[160:161]
	s_barrier
	ds_read_b128 v[146:149], v207 offset:16384
	ds_read_b128 v[150:153], v207 offset:17408
	ds_read_b128 v[166:169], v207 offset:18432
	ds_read_b128 v[170:173], v207 offset:19456
	ds_read_b128 v[174:177], v207 offset:20480
	ds_read_b128 v[188:191], v207 offset:21504
	ds_read_b128 v[192:195], v207 offset:22528
	ds_read_b128 v[196:199], v207 offset:23552
	global_load_lds_dwordx4 v[182:183], off
	v_lshl_add_u64 v[220:221], s[24:25], 0, v[158:159]
	s_mov_b32 m0, s80
	s_nop 0
	global_load_lds_dwordx4 v[220:221], off
	s_barrier
	s_waitcnt lgkmcnt(0)
	s_setprio 1
	v_mfma_f32_16x16x32_bf16 v[62:65], v[130:133], v[146:149], v[62:65]
	v_mfma_f32_16x16x32_bf16 v[58:61], v[138:141], v[146:149], v[58:61]
	v_mfma_f32_16x16x32_bf16 v[46:49], v[130:133], v[166:169], v[46:49]
	v_mfma_f32_16x16x32_bf16 v[42:45], v[138:141], v[166:169], v[42:45]
	v_mfma_f32_16x16x32_bf16 v[30:33], v[130:133], v[174:177], v[30:33]
	v_mfma_f32_16x16x32_bf16 v[26:29], v[138:141], v[174:177], v[26:29]
	v_mfma_f32_16x16x32_bf16 v[14:17], v[130:133], v[192:195], v[14:17]
	v_mfma_f32_16x16x32_bf16 v[10:13], v[138:141], v[192:195], v[10:13]
	v_mfma_f32_16x16x32_bf16 v[62:65], v[134:137], v[150:153], v[62:65]
	v_mfma_f32_16x16x32_bf16 v[58:61], v[142:145], v[150:153], v[58:61]
	v_mfma_f32_16x16x32_bf16 v[46:49], v[134:137], v[170:173], v[46:49]
	v_mfma_f32_16x16x32_bf16 v[42:45], v[142:145], v[170:173], v[42:45]
	v_mfma_f32_16x16x32_bf16 v[30:33], v[134:137], v[188:191], v[30:33]
	v_mfma_f32_16x16x32_bf16 v[26:29], v[142:145], v[188:191], v[26:29]
	v_mfma_f32_16x16x32_bf16 v[14:17], v[134:137], v[196:199], v[14:17]
	v_mfma_f32_16x16x32_bf16 v[10:13], v[142:145], v[196:199], v[10:13]
	s_setprio 0
	s_barrier
; #define PG8_STAGE(bufoff, gbase) PG8_STAGE_(bufoff, gbase, voffA)
; #define PG8_STAGEB(bufoff, gbase) PG8_STAGE_(bufoff, gbase, voffB)
; #define PG8_LDA(dst, b, h) do { _Pragma("unroll") for (int m = 0; m < 4; ++m) _Pragma("unroll") for (int k = 0; k < 2; ++k) dst[m][k] = *(const LAS bf16x8*)(lds + PG8_SA(b, h) + aoff + m * 2048 + k * 1024); } while (0)
; #define PG8_LDB(dst, b, h) do { _Pragma("unroll") for (int n = 0; n < 2; ++n) _Pragma("unroll") for (int k = 0; k < 2; ++k) dst[n][k] = *(const LAS bf16x8*)(lds + PG8_SB(b, h) + boff + n * 2048 + k * 1024); } while (0)
; #define PG8_MMA(ai, bj, At, Bt) do { __builtin_amdgcn_s_setprio(1); _Pragma("unroll") for (int m = 0; m < 4; ++m) _Pragma("unroll") for (int n = 0; n < 2; ++n) _Pragma("unroll") for (int k = 0; k < 2; ++k) \
;         acc[ai][bj][m][n] = __builtin_amdgcn_mfma_f32_16x16x32_bf16(Bt[n][k], At[m][k], acc[ai][bj][m][n], 0, 0, 0); __builtin_amdgcn_s_setprio(0); } while (0)
; #define PG8_WAIT_V(n) asm volatile("s_waitcnt vmcnt(" #n ")" ::: "memory")
; #define PG8_WAIT_L(n) asm volatile("s_waitcnt lgkmcnt(" #n ")" ::: "memory")
; #define PG8_BAR __builtin_amdgcn_s_barrier()
; #define PG8_SCHED __builtin_amdgcn_sched_barrier(0)
; template <class Epi>
; __device__ __forceinline__ void gemm_phase(LAS unsigned char* lds, const Gemm g, const StaticOrder& S, const Epi& E) {
;     ...
;             PG8_LDA(At, 0, 1); PG8_STAGE(PG8_SA(0, 0), a2);
;             PG8_BAR; PG8_WAIT_L(0); PG8_MMA(1, 0, At, B0); PG8_BAR; PG8_SCHED;
;             PG8_STAGEB(PG8_SB(0, 1), b2 + hstep);
;             PG8_WAIT_V(6); PG8_BAR; PG8_MMA(1, 1, At, B1); PG8_BAR;
;             PG8_LDB(B0, 1, 0); PG8_SCHED; PG8_LDA(At, 1, 0); PG8_STAGE(PG8_SA(0, 1), a2 + hstep);
;             PG8_WAIT_L(8); PG8_BAR; PG8_WAIT_L(0); PG8_MMA(0, 0, At, B0); PG8_BAR; PG8_SCHED;
;             PG8_LDB(B1, 1, 1); PG8_STAGEB(PG8_SB(1, 0), b3);
;             PG8_BAR; PG8_WAIT_L(0); PG8_MMA(0, 1, At, B1); PG8_BAR;
;             PG8_LDA(At, 1, 1); PG8_STAGE(PG8_SA(1, 0), a3);
;             PG8_BAR; PG8_WAIT_L(0); PG8_MMA(1, 0, At, B0); PG8_BAR; PG8_SCHED;
;             PG8_STAGEB(PG8_SB(1, 1), b3 + hstep);
;             PG8_WAIT_V(6); PG8_BAR; PG8_MMA(1, 1, At, B1); PG8_BAR;
	s_add_u32 s58, s20, 0x20000
	s_addc_u32 s59, s21, 0
	s_add_i32 s90, s90, s42
	v_lshl_add_u64 v[130:131], s[58:59], 0, v[0:1]
	s_mov_b32 m0, s90
	s_nop 0
	global_load_lds_dwordx4 v[130:131], off
	v_lshl_add_u64 v[130:131], s[58:59], 0, v[156:157]
	s_add_i32 m0, s90, 0x2000
	s_nop 0
	global_load_lds_dwordx4 v[130:131], off
	s_waitcnt vmcnt(6)
	s_barrier
	s_setprio 1
	v_mfma_f32_16x16x32_bf16 v[54:57], v[200:203], v[146:149], v[54:57]
	v_mfma_f32_16x16x32_bf16 v[50:53], v[212:215], v[146:149], v[50:53]
	v_mfma_f32_16x16x32_bf16 v[38:41], v[200:203], v[166:169], v[38:41]
	v_mfma_f32_16x16x32_bf16 v[34:37], v[212:215], v[166:169], v[34:37]
	v_mfma_f32_16x16x32_bf16 v[22:25], v[200:203], v[174:177], v[22:25]
	v_mfma_f32_16x16x32_bf16 v[18:21], v[212:215], v[174:177], v[18:21]
	v_mfma_f32_16x16x32_bf16 v[6:9], v[200:203], v[192:195], v[6:9]
	v_mfma_f32_16x16x32_bf16 v[2:5], v[212:215], v[192:195], v[2:5]
	v_mfma_f32_16x16x32_bf16 v[54:57], v[208:211], v[150:153], v[54:57]
	v_mfma_f32_16x16x32_bf16 v[50:53], v[216:219], v[150:153], v[50:53]
	v_mfma_f32_16x16x32_bf16 v[38:41], v[208:211], v[170:173], v[38:41]
	v_mfma_f32_16x16x32_bf16 v[34:37], v[216:219], v[170:173], v[34:37]
	v_mfma_f32_16x16x32_bf16 v[22:25], v[208:211], v[188:191], v[22:25]
	v_mfma_f32_16x16x32_bf16 v[18:21], v[216:219], v[188:191], v[18:21]
	v_mfma_f32_16x16x32_bf16 v[6:9], v[208:211], v[196:199], v[6:9]
	v_mfma_f32_16x16x32_bf16 v[2:5], v[216:219], v[196:199], v[2:5]
	s_setprio 0
	s_add_i32 s58, 0, 0x18000
	v_add_u32_e32 v142, s58, v206
	s_barrier
	ds_read_b128 v[130:133], v142
	ds_read_b128 v[134:137], v142 offset:1024
	ds_read_b128 v[138:141], v142 offset:2048
	ds_read_b128 v[142:145], v142 offset:3072
	s_add_u32 s24, s24, 0x20000
	s_addc_u32 s25, s25, 0
	s_mov_b32 m0, s81
	v_lshl_add_u64 v[200:201], s[24:25], 0, v[160:161]
	ds_read_b128 v[146:149], v207 offset:32768
	ds_read_b128 v[150:153], v207 offset:33792
	ds_read_b128 v[166:169], v207 offset:34816
	ds_read_b128 v[170:173], v207 offset:35840
	ds_read_b128 v[174:177], v207 offset:36864
	ds_read_b128 v[188:191], v207 offset:37888
	ds_read_b128 v[192:195], v207 offset:38912
	ds_read_b128 v[196:199], v207 offset:39936
	global_load_lds_dwordx4 v[200:201], off
	v_lshl_add_u64 v[200:201], s[24:25], 0, v[158:159]
	s_mov_b32 m0, s34
	s_nop 0
	global_load_lds_dwordx4 v[200:201], off
	s_waitcnt lgkmcnt(8)
	s_barrier
	s_waitcnt lgkmcnt(0)
	s_setprio 1
	v_mfma_f32_16x16x32_bf16 v[126:129], v[130:133], v[146:149], v[126:129]
	v_mfma_f32_16x16x32_bf16 v[122:125], v[138:141], v[146:149], v[122:125]
	v_mfma_f32_16x16x32_bf16 v[110:113], v[130:133], v[166:169], v[110:113]
	v_mfma_f32_16x16x32_bf16 v[106:109], v[138:141], v[166:169], v[106:109]
	v_mfma_f32_16x16x32_bf16 v[94:97], v[130:133], v[174:177], v[94:97]
	v_mfma_f32_16x16x32_bf16 v[90:93], v[138:141], v[174:177], v[90:93]
	v_mfma_f32_16x16x32_bf16 v[78:81], v[130:133], v[192:195], v[78:81]
	v_mfma_f32_16x16x32_bf16 v[74:77], v[138:141], v[192:195], v[74:77]
	v_mfma_f32_16x16x32_bf16 v[126:129], v[134:137], v[150:153], v[126:129]
	v_mfma_f32_16x16x32_bf16 v[122:125], v[142:145], v[150:153], v[122:125]
	v_mfma_f32_16x16x32_bf16 v[110:113], v[134:137], v[170:173], v[110:113]
	v_mfma_f32_16x16x32_bf16 v[106:109], v[142:145], v[170:173], v[106:109]
	v_mfma_f32_16x16x32_bf16 v[94:97], v[134:137], v[188:191], v[94:97]
	v_mfma_f32_16x16x32_bf16 v[90:93], v[142:145], v[188:191], v[90:93]
	v_mfma_f32_16x16x32_bf16 v[78:81], v[134:137], v[196:199], v[78:81]
	v_mfma_f32_16x16x32_bf16 v[74:77], v[142:145], v[196:199], v[74:77]
	s_setprio 0
	s_barrier
	s_add_i32 s24, 0, 0x1c000
	s_add_i32 s25, s58, s42
	v_add_u32_e32 v216, s24, v206
	v_lshl_add_u64 v[154:155], v[154:155], 0, s[16:17]
	s_mov_b32 m0, s25
	ds_read_b128 v[200:203], v216
	ds_read_b128 v[208:211], v216 offset:1024
	ds_read_b128 v[212:215], v216 offset:2048
	ds_read_b128 v[216:219], v216 offset:3072
	global_load_lds_dwordx4 v[154:155], off
	v_lshl_add_u64 v[154:155], v[178:179], 0, s[16:17]
	s_add_i32 m0, s25, 0x2000
	s_nop 0
	global_load_lds_dwordx4 v[154:155], off
	s_barrier
	s_waitcnt lgkmcnt(0)
	s_setprio 1
	v_mfma_f32_16x16x32_bf16 v[118:121], v[200:203], v[146:149], v[118:121]
	v_mfma_f32_16x16x32_bf16 v[114:117], v[212:215], v[146:149], v[114:117]
	v_mfma_f32_16x16x32_bf16 v[102:105], v[200:203], v[166:169], v[102:105]
	v_mfma_f32_16x16x32_bf16 v[98:101], v[212:215], v[166:169], v[98:101]
	v_mfma_f32_16x16x32_bf16 v[86:89], v[200:203], v[174:177], v[86:89]
	v_mfma_f32_16x16x32_bf16 v[82:85], v[212:215], v[174:177], v[82:85]
	v_mfma_f32_16x16x32_bf16 v[70:73], v[200:203], v[192:195], v[70:73]
	v_mfma_f32_16x16x32_bf16 v[66:69], v[212:215], v[192:195], v[66:69]
	v_mfma_f32_16x16x32_bf16 v[118:121], v[208:211], v[150:153], v[118:121]
	v_mfma_f32_16x16x32_bf16 v[114:117], v[216:219], v[150:153], v[114:117]
	v_mfma_f32_16x16x32_bf16 v[102:105], v[208:211], v[170:173], v[102:105]
	v_mfma_f32_16x16x32_bf16 v[98:101], v[216:219], v[170:173], v[98:101]
	v_mfma_f32_16x16x32_bf16 v[86:89], v[208:211], v[188:191], v[86:89]
	v_mfma_f32_16x16x32_bf16 v[82:85], v[216:219], v[188:191], v[82:85]
	v_mfma_f32_16x16x32_bf16 v[70:73], v[208:211], v[196:199], v[70:73]
	v_mfma_f32_16x16x32_bf16 v[66:69], v[216:219], v[196:199], v[66:69]
	s_setprio 0
	s_mov_b32 m0, s82
	v_lshl_add_u64 v[154:155], v[182:183], 0, s[16:17]
	s_barrier
	ds_read_b128 v[146:149], v207 offset:49152
	ds_read_b128 v[150:153], v207 offset:50176
	ds_read_b128 v[166:169], v207 offset:51200
	ds_read_b128 v[170:173], v207 offset:52224
	ds_read_b128 v[174:177], v207 offset:53248
	ds_read_b128 v[188:191], v207 offset:54272
	ds_read_b128 v[192:195], v207 offset:55296
	ds_read_b128 v[196:199], v207 offset:56320
	global_load_lds_dwordx4 v[154:155], off
	v_lshl_add_u64 v[154:155], v[220:221], 0, s[16:17]
	s_mov_b32 m0, s83
	s_nop 0
	global_load_lds_dwordx4 v[154:155], off
	s_barrier
; __device__ __forceinline__ float sigmoidf_(float x) { return __builtin_amdgcn_rcpf(1.f + __expf(-x)); }
; __device__ __forceinline__ float siluf_(float x) { return x * sigmoidf_(x); }
; __device__ __forceinline__ int fresh_tid() { int t = threadIdx.x; asm volatile("" : "+v"(t)); return t; }
; #define PG8_STAGEB(bufoff, gbase) PG8_STAGE_(bufoff, gbase, voffB)
; #define PG8_MMA(ai, bj, At, Bt) do { __builtin_amdgcn_s_setprio(1); _Pragma("unroll") for (int m = 0; m < 4; ++m) _Pragma("unroll") for (int n = 0; n < 2; ++n) _Pragma("unroll") for (int k = 0; k < 2; ++k) \
;         acc[ai][bj][m][n] = __builtin_amdgcn_mfma_f32_16x16x32_bf16(Bt[n][k], At[m][k], acc[ai][bj][m][n], 0, 0, 0); __builtin_amdgcn_s_setprio(0); } while (0)
; #define PG8_WAIT_V(n) asm volatile("s_waitcnt vmcnt(" #n ")" ::: "memory")
; #define PG8_BAR __builtin_amdgcn_s_barrier()
; template <class Epi>
; __device__ __forceinline__ void gemm_phase(LAS unsigned char* lds, const Gemm g, const StaticOrder& S, const Epi& E) {
;     ...
;             PG8_BAR; PG8_WAIT_L(0); PG8_MMA(1, 0, At, B0); PG8_BAR; PG8_SCHED;
;             PG8_STAGEB(PG8_SB(1, 1), b3 + hstep);
;             PG8_WAIT_V(6); PG8_BAR; PG8_MMA(1, 1, At, B1); PG8_BAR;
;         }
;         { const int t2 = fresh_tid(); const int w2 = __builtin_amdgcn_readfirstlane(t2 >> 6); E(acc, cur, w2 >> 2, w2 & 3, t2 & 15, (t2 >> 4) & 3); }
;         if (!has_next) break;
;     __device__ __forceinline__ void operator()(AccT& acc, const Unit& u, int wr, int wc, int fr, int fq) const {
;         int row0 = u.pm * 256 + wr * 64 + fr, col0 = u.pn * 256 + wc * 32 + 8 * fq;
;         asm volatile("" : "+v"(row0), "+v"(col0));
; #pragma unroll
;         for (int ai = 0; ai < 2; ++ai)
; #pragma unroll
;             for (int m = 0; m < 4; ++m) { const size_t row = (size_t)(row0 + ai * 128 + m * 16);
; #pragma unroll
;                 for (int bj = 0; bj < 2; ++bj) { const int c = col0 + bj * 128;
;                     float y8[8], z8[8], o8[8]; ld8(yd + row * 512 + c, y8); ld8(proj + row * NP + O_DZ + c, z8);
;                     const f32x4 b0 = *(const f32x4*)(gb + c), b1 = *(const f32x4*)(gb + c + 4);
; #pragma unroll
;                     for (int e = 0; e < 4; ++e) { o8[e] = y8[e] * sigmoidf_(acc[ai][bj][m][0][e] + b0[e]) * siluf_(z8[e]); o8[4 + e] = y8[4 + e] * sigmoidf_(acc[ai][bj][m][1][e] + b1[e]) * siluf_(z8[4 + e]); }
	s_waitcnt lgkmcnt(0)
	s_setprio 1
	v_mfma_f32_16x16x32_bf16 v[62:65], v[130:133], v[146:149], v[62:65]
	v_mfma_f32_16x16x32_bf16 v[58:61], v[138:141], v[146:149], v[58:61]
	v_mfma_f32_16x16x32_bf16 v[46:49], v[130:133], v[166:169], v[46:49]
	v_mfma_f32_16x16x32_bf16 v[42:45], v[138:141], v[166:169], v[42:45]
	v_mfma_f32_16x16x32_bf16 v[30:33], v[130:133], v[174:177], v[30:33]
	v_mfma_f32_16x16x32_bf16 v[26:29], v[138:141], v[174:177], v[26:29]
	v_mfma_f32_16x16x32_bf16 v[14:17], v[130:133], v[192:195], v[14:17]
	v_mfma_f32_16x16x32_bf16 v[10:13], v[138:141], v[192:195], v[10:13]
	v_mfma_f32_16x16x32_bf16 v[62:65], v[134:137], v[150:153], v[62:65]
	v_mfma_f32_16x16x32_bf16 v[58:61], v[142:145], v[150:153], v[58:61]
	v_mfma_f32_16x16x32_bf16 v[46:49], v[134:137], v[170:173], v[46:49]
	v_mfma_f32_16x16x32_bf16 v[42:45], v[142:145], v[170:173], v[42:45]
	v_mfma_f32_16x16x32_bf16 v[30:33], v[134:137], v[188:191], v[30:33]
	v_mfma_f32_16x16x32_bf16 v[26:29], v[142:145], v[188:191], v[26:29]
	v_mfma_f32_16x16x32_bf16 v[14:17], v[134:137], v[196:199], v[14:17]
	v_mfma_f32_16x16x32_bf16 v[10:13], v[142:145], v[196:199], v[10:13]
	s_setprio 0
	s_barrier
	s_add_u32 s20, s20, 0x20080
	s_addc_u32 s21, s21, 0
	s_add_i32 s24, s24, s42
	v_lshl_add_u64 v[130:131], s[20:21], 0, v[0:1]
	s_mov_b32 m0, s24
	s_nop 0
	global_load_lds_dwordx4 v[130:131], off
	v_lshl_add_u64 v[130:131], s[20:21], 0, v[156:157]
	s_add_i32 m0, s24, 0x2000
	s_nop 0
	global_load_lds_dwordx4 v[130:131], off
	s_waitcnt vmcnt(6)
	s_barrier
	s_setprio 1
	v_mfma_f32_16x16x32_bf16 v[54:57], v[200:203], v[146:149], v[54:57]
	v_mfma_f32_16x16x32_bf16 v[50:53], v[212:215], v[146:149], v[50:53]
	v_mfma_f32_16x16x32_bf16 v[38:41], v[200:203], v[166:169], v[38:41]
	v_mfma_f32_16x16x32_bf16 v[34:37], v[212:215], v[166:169], v[34:37]
	v_mfma_f32_16x16x32_bf16 v[22:25], v[200:203], v[174:177], v[22:25]
	v_mfma_f32_16x16x32_bf16 v[18:21], v[212:215], v[174:177], v[18:21]
	v_mfma_f32_16x16x32_bf16 v[6:9], v[200:203], v[192:195], v[6:9]
	v_mfma_f32_16x16x32_bf16 v[2:5], v[212:215], v[192:195], v[2:5]
	v_mfma_f32_16x16x32_bf16 v[54:57], v[208:211], v[150:153], v[54:57]
	v_mfma_f32_16x16x32_bf16 v[50:53], v[216:219], v[150:153], v[50:53]
	v_mfma_f32_16x16x32_bf16 v[38:41], v[208:211], v[170:173], v[38:41]
	v_mfma_f32_16x16x32_bf16 v[34:37], v[216:219], v[170:173], v[34:37]
	v_mfma_f32_16x16x32_bf16 v[22:25], v[208:211], v[188:191], v[22:25]
	v_mfma_f32_16x16x32_bf16 v[18:21], v[216:219], v[188:191], v[18:21]
	v_mfma_f32_16x16x32_bf16 v[6:9], v[208:211], v[196:199], v[6:9]
	v_mfma_f32_16x16x32_bf16 v[2:5], v[216:219], v[196:199], v[2:5]
	s_setprio 0
	s_add_i32 s89, s89, 2
	s_add_u32 s6, s6, 0x100
	s_addc_u32 s7, s7, 0
	s_add_u32 s87, s87, 0x100
	s_addc_u32 s88, s88, 0
	s_cmp_gt_u32 s89, 5
	s_barrier
	s_cbranch_scc0 .LBB0_1302
	v_mov_b32_e32 v130, v250
	s_lshl_b32 s7, s86, 8
	v_readfirstlane_b32 s6, v130
	s_ashr_i32 s20, s6, 2
	s_andn2_b32 s20, s20, 63
	s_lshr_b32 s6, s6, 1
	s_add_i32 s20, s20, s7
	s_lshl_b32 s7, s85, 8
	s_and_b32 s6, s6, 0x60
	v_and_or_b32 v170, v130, 15, s20
	s_or_b32 s6, s6, s7
	v_lshrrev_b32_e32 v130, 1, v130
	v_and_or_b32 v138, v130, 24, s6
	v_mov_b64_e32 v[172:173], s[44:45]
	v_ashrrev_i32_e32 v171, 31, v170
	v_lshlrev_b64 v[130:131], 10, v[170:171]
	v_ashrrev_i32_e32 v139, 31, v138
	v_lshl_add_u64 v[130:131], s[0:1], 0, v[130:131]
	v_lshlrev_b64 v[166:167], 1, v[138:139]
	v_lshl_add_u64 v[174:175], v[130:131], 0, v[166:167]
	v_mad_i64_i32 v[130:131], s[6:7], v170, s26, v[172:173]
	v_lshl_add_u64 v[130:131], v[130:131], 0, v[166:167]
	s_mov_b64 s[20:21], 0x4510
	v_lshl_add_u64 v[178:179], v[130:131], 0, s[20:21]
	v_add_co_u32_e32 v130, vcc, s12, v130
	v_lshl_add_u64 v[168:169], v[138:139], 2, s[46:47]
	s_nop 0
	v_addc_co_u32_e32 v131, vcc, 0, v131, vcc
	v_lshlrev_b64 v[176:177], 12, v[170:171]
	v_lshl_add_u64 v[176:177], s[48:49], 0, v[176:177]
	v_lshl_add_u64 v[176:177], v[176:177], 0, v[166:167]
	global_load_dwordx4 v[222:225], v[168:169], off
	global_load_dwordx4 v[226:229], v[168:169], off offset:16
	global_load_dwordx4 v[230:233], v[168:169], off offset:512
	global_load_dwordx4 v[234:237], v[168:169], off offset:528
	s_mov_b32 s85, s52
	s_mov_b32 s86, s54
	s_mov_b32 s89, 0x42b17218
	s_brev_b32 s90, 18
	global_load_dwordx4 v[130:133], v[174:175], off
	global_load_dwordx4 v[134:137], v[174:175], off offset:256
	global_load_dwordx4 v[138:141], v[178:179], off
	global_load_dwordx4 v[142:145], v[178:179], off offset:256
	s_mov_b64 s[6:7], 0x4000
	v_lshl_add_u64 v[174:175], v[174:175], 0, s[6:7]
	s_mov_b64 s[6:7], 0x8a000
	v_lshl_add_u64 v[178:179], v[178:179], 0, s[6:7]
	global_load_dwordx4 v[188:191], v[174:175], off
	global_load_dwordx4 v[192:195], v[174:175], off offset:256
	global_load_dwordx4 v[196:199], v[178:179], off
	global_load_dwordx4 v[200:203], v[178:179], off offset:256
	s_mov_b64 s[6:7], 0x4000
	v_lshl_add_u64 v[174:175], v[174:175], 0, s[6:7]
	s_mov_b64 s[6:7], 0x8a000
	v_lshl_add_u64 v[178:179], v[178:179], 0, s[6:7]
	global_load_dwordx4 v[208:211], v[174:175], off
	global_load_dwordx4 v[212:215], v[174:175], off offset:256
	global_load_dwordx4 v[216:219], v[178:179], off
	global_load_dwordx4 v[150:153], v[178:179], off offset:256
	s_mov_b64 s[6:7], 0x4000
	v_lshl_add_u64 v[174:175], v[174:175], 0, s[6:7]
	s_mov_b64 s[6:7], 0x8a000
	v_lshl_add_u64 v[178:179], v[178:179], 0, s[6:7]
	s_waitcnt vmcnt(8)
; __device__ __forceinline__ float sigmoidf_(float x) { return __builtin_amdgcn_rcpf(1.f + __expf(-x)); }
; __device__ __forceinline__ float siluf_(float x) { return x * sigmoidf_(x); }
;     __device__ __forceinline__ void operator()(AccT& acc, const Unit& u, int wr, int wc, int fr, int fq) const {
;     ...
;         for (int ai = 0; ai < 2; ++ai)
; #pragma unroll
;             for (int m = 0; m < 4; ++m) { const size_t row = (size_t)(row0 + ai * 128 + m * 16);
; #pragma unroll
;                 for (int bj = 0; bj < 2; ++bj) { const int c = col0 + bj * 128;
;                     float y8[8], z8[8], o8[8]; ld8(yd + row * 512 + c, y8); ld8(proj + row * NP + O_DZ + c, z8);
;                     const f32x4 b0 = *(const f32x4*)(gb + c), b1 = *(const f32x4*)(gb + c + 4);
; #pragma unroll
;                     for (int e = 0; e < 4; ++e) { o8[e] = y8[e] * sigmoidf_(acc[ai][bj][m][0][e] + b0[e]) * siluf_(z8[e]); o8[4 + e] = y8[4 + e] * sigmoidf_(acc[ai][bj][m][1][e] + b1[e]) * siluf_(z8[4 + e]); }
;                     st8(ys + row * DM + 1536 + c, o8); } }
	v_add_f32_e32 v126, v126, v222
	v_add_f32_e32 v127, v127, v223
	v_add_f32_e32 v128, v128, v224
	v_add_f32_e32 v129, v129, v225
	v_lshlrev_b32_e32 v146, 16, v138
	v_and_b32_e32 v149, 0xffff0000, v138
	v_lshlrev_b32_e32 v168, 16, v139
	v_and_b32_e32 v171, 0xffff0000, v139
	v_mul_f32_e32 v126, 0xbfb8aa3b, v126
	v_mul_f32_e32 v127, 0xbfb8aa3b, v127
	v_mul_f32_e32 v128, 0xbfb8aa3b, v128
	v_mul_f32_e32 v129, 0xbfb8aa3b, v129
	v_mul_f32_e32 v147, 0xbfb8aa3b, v146
	v_mul_f32_e32 v166, 0xbfb8aa3b, v149
	v_mul_f32_e32 v169, 0xbfb8aa3b, v168
	v_mul_f32_e32 v172, 0xbfb8aa3b, v171
	v_exp_f32_e32 v126, v126
	v_exp_f32_e32 v127, v127
	v_exp_f32_e32 v128, v128
	v_exp_f32_e32 v129, v129
	v_exp_f32_e32 v147, v147
	v_exp_f32_e32 v166, v166
	v_exp_f32_e32 v169, v169
	v_exp_f32_e32 v172, v172
	v_lshlrev_b32_e32 v148, 16, v130
	v_and_b32_e32 v167, 0xffff0000, v130
	v_lshlrev_b32_e32 v170, 16, v131
	v_and_b32_e32 v173, 0xffff0000, v131
	v_add_f32_e32 v126, 1.0, v126
	v_add_f32_e32 v127, 1.0, v127
	v_add_f32_e32 v128, 1.0, v128
	v_add_f32_e32 v129, 1.0, v129
	v_add_f32_e32 v147, 1.0, v147
	v_add_f32_e32 v166, 1.0, v166
	v_add_f32_e32 v169, 1.0, v169
	v_add_f32_e32 v172, 1.0, v172
	v_rcp_f32_e32 v126, v126
	v_rcp_f32_e32 v127, v127
	v_rcp_f32_e32 v128, v128
	v_rcp_f32_e32 v129, v129
	v_rcp_f32_e32 v147, v147
	v_rcp_f32_e32 v166, v166
	v_rcp_f32_e32 v169, v169
	v_rcp_f32_e32 v172, v172
	v_mul_f32_e32 v148, v126, v148
	v_mul_f32_e32 v167, v127, v167
	v_mul_f32_e32 v170, v128, v170
	v_mul_f32_e32 v173, v129, v173
	v_mul_f32_e32 v147, v147, v146
	v_mul_f32_e32 v166, v166, v149
	v_mul_f32_e32 v169, v169, v168
	v_mul_f32_e32 v172, v172, v171
	v_mul_f32_e32 v126, v147, v148
	v_mul_f32_e32 v127, v166, v167
	v_mul_f32_e32 v128, v169, v170
	v_mul_f32_e32 v129, v172, v173
	v_add_f32_e32 v122, v122, v226
	v_add_f32_e32 v123, v123, v227
	v_add_f32_e32 v124, v124, v228
	v_add_f32_e32 v125, v125, v229
	v_lshlrev_b32_e32 v146, 16, v140
	v_and_b32_e32 v149, 0xffff0000, v140
	v_lshlrev_b32_e32 v168, 16, v141
	v_and_b32_e32 v171, 0xffff0000, v141
	v_mul_f32_e32 v122, 0xbfb8aa3b, v122
	v_mul_f32_e32 v123, 0xbfb8aa3b, v123
	v_mul_f32_e32 v124, 0xbfb8aa3b, v124
	v_mul_f32_e32 v125, 0xbfb8aa3b, v125
	v_mul_f32_e32 v147, 0xbfb8aa3b, v146
	v_mul_f32_e32 v166, 0xbfb8aa3b, v149
	v_mul_f32_e32 v169, 0xbfb8aa3b, v168
	v_mul_f32_e32 v172, 0xbfb8aa3b, v171
	v_exp_f32_e32 v122, v122
	v_exp_f32_e32 v123, v123
	v_exp_f32_e32 v124, v124
	v_exp_f32_e32 v125, v125
	v_exp_f32_e32 v147, v147
	v_exp_f32_e32 v166, v166
	v_exp_f32_e32 v169, v169
	v_exp_f32_e32 v172, v172
	v_lshlrev_b32_e32 v148, 16, v132
	v_and_b32_e32 v167, 0xffff0000, v132
	v_lshlrev_b32_e32 v170, 16, v133
	v_and_b32_e32 v173, 0xffff0000, v133
	v_add_f32_e32 v122, 1.0, v122
	v_add_f32_e32 v123, 1.0, v123
	v_add_f32_e32 v124, 1.0, v124
	v_add_f32_e32 v125, 1.0, v125
	v_add_f32_e32 v147, 1.0, v147
	v_add_f32_e32 v166, 1.0, v166
	v_add_f32_e32 v169, 1.0, v169
	v_add_f32_e32 v172, 1.0, v172
	v_rcp_f32_e32 v122, v122
	v_rcp_f32_e32 v123, v123
	v_rcp_f32_e32 v124, v124
	v_rcp_f32_e32 v125, v125
	v_rcp_f32_e32 v147, v147
	v_rcp_f32_e32 v166, v166
	v_rcp_f32_e32 v169, v169
	v_rcp_f32_e32 v172, v172
	v_mul_f32_e32 v148, v122, v148
	v_mul_f32_e32 v167, v123, v167
	v_mul_f32_e32 v170, v124, v170
	v_mul_f32_e32 v173, v125, v173
	v_mul_f32_e32 v147, v147, v146
	v_mul_f32_e32 v166, v166, v149
	v_mul_f32_e32 v169, v169, v168
	v_mul_f32_e32 v172, v172, v171
	v_mul_f32_e32 v122, v147, v148
	v_mul_f32_e32 v123, v166, v167
	v_mul_f32_e32 v124, v169, v170
	v_mul_f32_e32 v125, v172, v173
	v_cvt_pk_bf16_f32 v130, v126, v127
	v_cvt_pk_bf16_f32 v131, v128, v129
	v_cvt_pk_bf16_f32 v132, v122, v123
	v_cvt_pk_bf16_f32 v133, v124, v125
	global_store_dwordx4 v[176:177], v[130:133], off offset:3072
	v_add_f32_e32 v118, v118, v230
	v_add_f32_e32 v119, v119, v231
	v_add_f32_e32 v120, v120, v232
	v_add_f32_e32 v121, v121, v233
	v_lshlrev_b32_e32 v146, 16, v142
	v_and_b32_e32 v149, 0xffff0000, v142
	v_lshlrev_b32_e32 v168, 16, v143
	v_and_b32_e32 v171, 0xffff0000, v143
	v_mul_f32_e32 v118, 0xbfb8aa3b, v118
	v_mul_f32_e32 v119, 0xbfb8aa3b, v119
	v_mul_f32_e32 v120, 0xbfb8aa3b, v120
	v_mul_f32_e32 v121, 0xbfb8aa3b, v121
	v_mul_f32_e32 v147, 0xbfb8aa3b, v146
	v_mul_f32_e32 v166, 0xbfb8aa3b, v149
	v_mul_f32_e32 v169, 0xbfb8aa3b, v168
	v_mul_f32_e32 v172, 0xbfb8aa3b, v171
	v_exp_f32_e32 v118, v118
	v_exp_f32_e32 v119, v119
	v_exp_f32_e32 v120, v120
	v_exp_f32_e32 v121, v121
	v_exp_f32_e32 v147, v147
	v_exp_f32_e32 v166, v166
	v_exp_f32_e32 v169, v169
	v_exp_f32_e32 v172, v172
	v_lshlrev_b32_e32 v148, 16, v134
	v_and_b32_e32 v167, 0xffff0000, v134
	v_lshlrev_b32_e32 v170, 16, v135
	v_and_b32_e32 v173, 0xffff0000, v135
	v_add_f32_e32 v118, 1.0, v118
	v_add_f32_e32 v119, 1.0, v119
	v_add_f32_e32 v120, 1.0, v120
	v_add_f32_e32 v121, 1.0, v121
	v_add_f32_e32 v147, 1.0, v147
	v_add_f32_e32 v166, 1.0, v166
	v_add_f32_e32 v169, 1.0, v169
	v_add_f32_e32 v172, 1.0, v172
	v_rcp_f32_e32 v118, v118
	v_rcp_f32_e32 v119, v119
	v_rcp_f32_e32 v120, v120
	v_rcp_f32_e32 v121, v121
	v_rcp_f32_e32 v147, v147
	v_rcp_f32_e32 v166, v166
	v_rcp_f32_e32 v169, v169
	v_rcp_f32_e32 v172, v172
	v_mul_f32_e32 v148, v118, v148
	v_mul_f32_e32 v167, v119, v167
	v_mul_f32_e32 v170, v120, v170
	v_mul_f32_e32 v173, v121, v173
	v_mul_f32_e32 v147, v147, v146
	v_mul_f32_e32 v166, v166, v149
	v_mul_f32_e32 v169, v169, v168
	v_mul_f32_e32 v172, v172, v171
	v_mul_f32_e32 v118, v147, v148
	v_mul_f32_e32 v119, v166, v167
	v_mul_f32_e32 v120, v169, v170
	v_mul_f32_e32 v121, v172, v173
	v_add_f32_e32 v114, v114, v234
	v_add_f32_e32 v115, v115, v235
	v_add_f32_e32 v116, v116, v236
	v_add_f32_e32 v117, v117, v237
; __device__ __forceinline__ float sigmoidf_(float x) { return __builtin_amdgcn_rcpf(1.f + __expf(-x)); }
; __device__ __forceinline__ float siluf_(float x) { return x * sigmoidf_(x); }
;     __device__ __forceinline__ void operator()(AccT& acc, const Unit& u, int wr, int wc, int fr, int fq) const {
;     ...
;         for (int ai = 0; ai < 2; ++ai)
; #pragma unroll
;             for (int m = 0; m < 4; ++m) { const size_t row = (size_t)(row0 + ai * 128 + m * 16);
; #pragma unroll
;                 for (int bj = 0; bj < 2; ++bj) { const int c = col0 + bj * 128;
;                     float y8[8], z8[8], o8[8]; ld8(yd + row * 512 + c, y8); ld8(proj + row * NP + O_DZ + c, z8);
;                     const f32x4 b0 = *(const f32x4*)(gb + c), b1 = *(const f32x4*)(gb + c + 4);
; #pragma unroll
;                     for (int e = 0; e < 4; ++e) { o8[e] = y8[e] * sigmoidf_(acc[ai][bj][m][0][e] + b0[e]) * siluf_(z8[e]); o8[4 + e] = y8[4 + e] * sigmoidf_(acc[ai][bj][m][1][e] + b1[e]) * siluf_(z8[4 + e]); }
;                     st8(ys + row * DM + 1536 + c, o8); } }
	v_lshlrev_b32_e32 v146, 16, v144
	v_and_b32_e32 v149, 0xffff0000, v144
	v_lshlrev_b32_e32 v168, 16, v145
	v_and_b32_e32 v171, 0xffff0000, v145
	v_mul_f32_e32 v114, 0xbfb8aa3b, v114
	v_mul_f32_e32 v115, 0xbfb8aa3b, v115
	v_mul_f32_e32 v116, 0xbfb8aa3b, v116
	v_mul_f32_e32 v117, 0xbfb8aa3b, v117
	v_mul_f32_e32 v147, 0xbfb8aa3b, v146
	v_mul_f32_e32 v166, 0xbfb8aa3b, v149
	v_mul_f32_e32 v169, 0xbfb8aa3b, v168
	v_mul_f32_e32 v172, 0xbfb8aa3b, v171
	v_exp_f32_e32 v114, v114
	v_exp_f32_e32 v115, v115
	v_exp_f32_e32 v116, v116
	v_exp_f32_e32 v117, v117
	v_exp_f32_e32 v147, v147
	v_exp_f32_e32 v166, v166
	v_exp_f32_e32 v169, v169
	v_exp_f32_e32 v172, v172
	v_lshlrev_b32_e32 v148, 16, v136
	v_and_b32_e32 v167, 0xffff0000, v136
	v_lshlrev_b32_e32 v170, 16, v137
	v_and_b32_e32 v173, 0xffff0000, v137
	v_add_f32_e32 v114, 1.0, v114
	v_add_f32_e32 v115, 1.0, v115
	v_add_f32_e32 v116, 1.0, v116
	v_add_f32_e32 v117, 1.0, v117
	v_add_f32_e32 v147, 1.0, v147
	v_add_f32_e32 v166, 1.0, v166
	v_add_f32_e32 v169, 1.0, v169
	v_add_f32_e32 v172, 1.0, v172
	v_rcp_f32_e32 v114, v114
	v_rcp_f32_e32 v115, v115
	v_rcp_f32_e32 v116, v116
	v_rcp_f32_e32 v117, v117
	v_rcp_f32_e32 v147, v147
	v_rcp_f32_e32 v166, v166
	v_rcp_f32_e32 v169, v169
	v_rcp_f32_e32 v172, v172
	v_mul_f32_e32 v148, v114, v148
	v_mul_f32_e32 v167, v115, v167
	v_mul_f32_e32 v170, v116, v170
	v_mul_f32_e32 v173, v117, v173
	v_mul_f32_e32 v147, v147, v146
	v_mul_f32_e32 v166, v166, v149
	v_mul_f32_e32 v169, v169, v168
	v_mul_f32_e32 v172, v172, v171
	v_mul_f32_e32 v114, v147, v148
	v_mul_f32_e32 v115, v166, v167
	v_mul_f32_e32 v116, v169, v170
	v_mul_f32_e32 v117, v172, v173
	v_cvt_pk_bf16_f32 v134, v118, v119
	v_cvt_pk_bf16_f32 v135, v120, v121
	v_cvt_pk_bf16_f32 v136, v114, v115
	v_cvt_pk_bf16_f32 v137, v116, v117
	global_store_dwordx4 v[176:177], v[134:137], off offset:3328
	s_mov_b64 s[6:7], 0x10000
	v_lshl_add_u64 v[176:177], v[176:177], 0, s[6:7]
	global_load_dwordx4 v[130:133], v[174:175], off
	global_load_dwordx4 v[134:137], v[174:175], off offset:256
	global_load_dwordx4 v[138:141], v[178:179], off
	global_load_dwordx4 v[142:145], v[178:179], off offset:256
	s_mov_b64 s[6:7], 0x14000
	v_lshl_add_u64 v[174:175], v[174:175], 0, s[6:7]
	s_mov_b64 s[6:7], 0x2b2000
	v_lshl_add_u64 v[178:179], v[178:179], 0, s[6:7]
	s_waitcnt vmcnt(10)
	v_add_f32_e32 v110, v110, v222
	v_add_f32_e32 v111, v111, v223
	v_add_f32_e32 v112, v112, v224
	v_add_f32_e32 v113, v113, v225
	v_lshlrev_b32_e32 v146, 16, v196
	v_and_b32_e32 v149, 0xffff0000, v196
	v_lshlrev_b32_e32 v168, 16, v197
	v_and_b32_e32 v171, 0xffff0000, v197
	v_mul_f32_e32 v110, 0xbfb8aa3b, v110
	v_mul_f32_e32 v111, 0xbfb8aa3b, v111
	v_mul_f32_e32 v112, 0xbfb8aa3b, v112
	v_mul_f32_e32 v113, 0xbfb8aa3b, v113
	v_mul_f32_e32 v147, 0xbfb8aa3b, v146
	v_mul_f32_e32 v166, 0xbfb8aa3b, v149
	v_mul_f32_e32 v169, 0xbfb8aa3b, v168
	v_mul_f32_e32 v172, 0xbfb8aa3b, v171
	v_exp_f32_e32 v110, v110
	v_exp_f32_e32 v111, v111
	v_exp_f32_e32 v112, v112
	v_exp_f32_e32 v113, v113
	v_exp_f32_e32 v147, v147
	v_exp_f32_e32 v166, v166
	v_exp_f32_e32 v169, v169
	v_exp_f32_e32 v172, v172
	v_lshlrev_b32_e32 v148, 16, v188
	v_and_b32_e32 v167, 0xffff0000, v188
	v_lshlrev_b32_e32 v170, 16, v189
	v_and_b32_e32 v173, 0xffff0000, v189
	v_add_f32_e32 v110, 1.0, v110
	v_add_f32_e32 v111, 1.0, v111
	v_add_f32_e32 v112, 1.0, v112
	v_add_f32_e32 v113, 1.0, v113
	v_add_f32_e32 v147, 1.0, v147
	v_add_f32_e32 v166, 1.0, v166
	v_add_f32_e32 v169, 1.0, v169
	v_add_f32_e32 v172, 1.0, v172
	v_rcp_f32_e32 v110, v110
	v_rcp_f32_e32 v111, v111
	v_rcp_f32_e32 v112, v112
	v_rcp_f32_e32 v113, v113
	v_rcp_f32_e32 v147, v147
	v_rcp_f32_e32 v166, v166
	v_rcp_f32_e32 v169, v169
	v_rcp_f32_e32 v172, v172
	v_mul_f32_e32 v148, v110, v148
	v_mul_f32_e32 v167, v111, v167
	v_mul_f32_e32 v170, v112, v170
	v_mul_f32_e32 v173, v113, v173
	v_mul_f32_e32 v147, v147, v146
	v_mul_f32_e32 v166, v166, v149
	v_mul_f32_e32 v169, v169, v168
	v_mul_f32_e32 v172, v172, v171
	v_mul_f32_e32 v110, v147, v148
	v_mul_f32_e32 v111, v166, v167
	v_mul_f32_e32 v112, v169, v170
	v_mul_f32_e32 v113, v172, v173
	v_add_f32_e32 v106, v106, v226
	v_add_f32_e32 v107, v107, v227
	v_add_f32_e32 v108, v108, v228
	v_add_f32_e32 v109, v109, v229
	v_lshlrev_b32_e32 v146, 16, v198
	v_and_b32_e32 v149, 0xffff0000, v198
	v_lshlrev_b32_e32 v168, 16, v199
	v_and_b32_e32 v171, 0xffff0000, v199
	v_mul_f32_e32 v106, 0xbfb8aa3b, v106
	v_mul_f32_e32 v107, 0xbfb8aa3b, v107
	v_mul_f32_e32 v108, 0xbfb8aa3b, v108
	v_mul_f32_e32 v109, 0xbfb8aa3b, v109
	v_mul_f32_e32 v147, 0xbfb8aa3b, v146
	v_mul_f32_e32 v166, 0xbfb8aa3b, v149
	v_mul_f32_e32 v169, 0xbfb8aa3b, v168
	v_mul_f32_e32 v172, 0xbfb8aa3b, v171
	v_exp_f32_e32 v106, v106
	v_exp_f32_e32 v107, v107
	v_exp_f32_e32 v108, v108
	v_exp_f32_e32 v109, v109
	v_exp_f32_e32 v147, v147
	v_exp_f32_e32 v166, v166
	v_exp_f32_e32 v169, v169
	v_exp_f32_e32 v172, v172
	v_lshlrev_b32_e32 v148, 16, v190
	v_and_b32_e32 v167, 0xffff0000, v190
	v_lshlrev_b32_e32 v170, 16, v191
	v_and_b32_e32 v173, 0xffff0000, v191
	v_add_f32_e32 v106, 1.0, v106
	v_add_f32_e32 v107, 1.0, v107
	v_add_f32_e32 v108, 1.0, v108
	v_add_f32_e32 v109, 1.0, v109
	v_add_f32_e32 v147, 1.0, v147
	v_add_f32_e32 v166, 1.0, v166
	v_add_f32_e32 v169, 1.0, v169
	v_add_f32_e32 v172, 1.0, v172
	v_rcp_f32_e32 v106, v106
	v_rcp_f32_e32 v107, v107
	v_rcp_f32_e32 v108, v108
	v_rcp_f32_e32 v109, v109
	v_rcp_f32_e32 v147, v147
	v_rcp_f32_e32 v166, v166
	v_rcp_f32_e32 v169, v169
	v_rcp_f32_e32 v172, v172
	v_mul_f32_e32 v148, v106, v148
	v_mul_f32_e32 v167, v107, v167
	v_mul_f32_e32 v170, v108, v170
	v_mul_f32_e32 v173, v109, v173
	v_mul_f32_e32 v147, v147, v146
; __device__ __forceinline__ float sigmoidf_(float x) { return __builtin_amdgcn_rcpf(1.f + __expf(-x)); }
; __device__ __forceinline__ float siluf_(float x) { return x * sigmoidf_(x); }
;     __device__ __forceinline__ void operator()(AccT& acc, const Unit& u, int wr, int wc, int fr, int fq) const {
;     ...
;         for (int ai = 0; ai < 2; ++ai)
; #pragma unroll
;             for (int m = 0; m < 4; ++m) { const size_t row = (size_t)(row0 + ai * 128 + m * 16);
; #pragma unroll
;                 for (int bj = 0; bj < 2; ++bj) { const int c = col0 + bj * 128;
;                     float y8[8], z8[8], o8[8]; ld8(yd + row * 512 + c, y8); ld8(proj + row * NP + O_DZ + c, z8);
;                     const f32x4 b0 = *(const f32x4*)(gb + c), b1 = *(const f32x4*)(gb + c + 4);
; #pragma unroll
;                     for (int e = 0; e < 4; ++e) { o8[e] = y8[e] * sigmoidf_(acc[ai][bj][m][0][e] + b0[e]) * siluf_(z8[e]); o8[4 + e] = y8[4 + e] * sigmoidf_(acc[ai][bj][m][1][e] + b1[e]) * siluf_(z8[4 + e]); }
;                     st8(ys + row * DM + 1536 + c, o8); } }
	v_mul_f32_e32 v166, v166, v149
	v_mul_f32_e32 v169, v169, v168
	v_mul_f32_e32 v172, v172, v171
	v_mul_f32_e32 v106, v147, v148
	v_mul_f32_e32 v107, v166, v167
	v_mul_f32_e32 v108, v169, v170
	v_mul_f32_e32 v109, v172, v173
	v_cvt_pk_bf16_f32 v188, v110, v111
	v_cvt_pk_bf16_f32 v189, v112, v113
	v_cvt_pk_bf16_f32 v190, v106, v107
	v_cvt_pk_bf16_f32 v191, v108, v109
	global_store_dwordx4 v[176:177], v[188:191], off offset:3072
	v_add_f32_e32 v102, v102, v230
	v_add_f32_e32 v103, v103, v231
	v_add_f32_e32 v104, v104, v232
	v_add_f32_e32 v105, v105, v233
	v_lshlrev_b32_e32 v146, 16, v200
	v_and_b32_e32 v149, 0xffff0000, v200
	v_lshlrev_b32_e32 v168, 16, v201
	v_and_b32_e32 v171, 0xffff0000, v201
	v_mul_f32_e32 v102, 0xbfb8aa3b, v102
	v_mul_f32_e32 v103, 0xbfb8aa3b, v103
	v_mul_f32_e32 v104, 0xbfb8aa3b, v104
	v_mul_f32_e32 v105, 0xbfb8aa3b, v105
	v_mul_f32_e32 v147, 0xbfb8aa3b, v146
	v_mul_f32_e32 v166, 0xbfb8aa3b, v149
	v_mul_f32_e32 v169, 0xbfb8aa3b, v168
	v_mul_f32_e32 v172, 0xbfb8aa3b, v171
	v_exp_f32_e32 v102, v102
	v_exp_f32_e32 v103, v103
	v_exp_f32_e32 v104, v104
	v_exp_f32_e32 v105, v105
	v_exp_f32_e32 v147, v147
	v_exp_f32_e32 v166, v166
	v_exp_f32_e32 v169, v169
	v_exp_f32_e32 v172, v172
	v_lshlrev_b32_e32 v148, 16, v192
	v_and_b32_e32 v167, 0xffff0000, v192
	v_lshlrev_b32_e32 v170, 16, v193
	v_and_b32_e32 v173, 0xffff0000, v193
	v_add_f32_e32 v102, 1.0, v102
	v_add_f32_e32 v103, 1.0, v103
	v_add_f32_e32 v104, 1.0, v104
	v_add_f32_e32 v105, 1.0, v105
	v_add_f32_e32 v147, 1.0, v147
	v_add_f32_e32 v166, 1.0, v166
	v_add_f32_e32 v169, 1.0, v169
	v_add_f32_e32 v172, 1.0, v172
	v_rcp_f32_e32 v102, v102
	v_rcp_f32_e32 v103, v103
	v_rcp_f32_e32 v104, v104
	v_rcp_f32_e32 v105, v105
	v_rcp_f32_e32 v147, v147
	v_rcp_f32_e32 v166, v166
	v_rcp_f32_e32 v169, v169
	v_rcp_f32_e32 v172, v172
	v_mul_f32_e32 v148, v102, v148
	v_mul_f32_e32 v167, v103, v167
	v_mul_f32_e32 v170, v104, v170
	v_mul_f32_e32 v173, v105, v173
	v_mul_f32_e32 v147, v147, v146
	v_mul_f32_e32 v166, v166, v149
	v_mul_f32_e32 v169, v169, v168
	v_mul_f32_e32 v172, v172, v171
	v_mul_f32_e32 v102, v147, v148
	v_mul_f32_e32 v103, v166, v167
	v_mul_f32_e32 v104, v169, v170
	v_mul_f32_e32 v105, v172, v173
	v_add_f32_e32 v98, v98, v234
	v_add_f32_e32 v99, v99, v235
	v_add_f32_e32 v100, v100, v236
	v_add_f32_e32 v101, v101, v237
	v_lshlrev_b32_e32 v146, 16, v202
	v_and_b32_e32 v149, 0xffff0000, v202
	v_lshlrev_b32_e32 v168, 16, v203
	v_and_b32_e32 v171, 0xffff0000, v203
	v_mul_f32_e32 v98, 0xbfb8aa3b, v98
	v_mul_f32_e32 v99, 0xbfb8aa3b, v99
	v_mul_f32_e32 v100, 0xbfb8aa3b, v100
	v_mul_f32_e32 v101, 0xbfb8aa3b, v101
	v_mul_f32_e32 v147, 0xbfb8aa3b, v146
	v_mul_f32_e32 v166, 0xbfb8aa3b, v149
	v_mul_f32_e32 v169, 0xbfb8aa3b, v168
	v_mul_f32_e32 v172, 0xbfb8aa3b, v171
	v_exp_f32_e32 v98, v98
	v_exp_f32_e32 v99, v99
	v_exp_f32_e32 v100, v100
	v_exp_f32_e32 v101, v101
	v_exp_f32_e32 v147, v147
	v_exp_f32_e32 v166, v166
	v_exp_f32_e32 v169, v169
	v_exp_f32_e32 v172, v172
	v_lshlrev_b32_e32 v148, 16, v194
	v_and_b32_e32 v167, 0xffff0000, v194
	v_lshlrev_b32_e32 v170, 16, v195
	v_and_b32_e32 v173, 0xffff0000, v195
	v_add_f32_e32 v98, 1.0, v98
	v_add_f32_e32 v99, 1.0, v99
	v_add_f32_e32 v100, 1.0, v100
	v_add_f32_e32 v101, 1.0, v101
	v_add_f32_e32 v147, 1.0, v147
	v_add_f32_e32 v166, 1.0, v166
	v_add_f32_e32 v169, 1.0, v169
	v_add_f32_e32 v172, 1.0, v172
	v_rcp_f32_e32 v98, v98
	v_rcp_f32_e32 v99, v99
	v_rcp_f32_e32 v100, v100
	v_rcp_f32_e32 v101, v101
	v_rcp_f32_e32 v147, v147
	v_rcp_f32_e32 v166, v166
	v_rcp_f32_e32 v169, v169
	v_rcp_f32_e32 v172, v172
	v_mul_f32_e32 v148, v98, v148
	v_mul_f32_e32 v167, v99, v167
	v_mul_f32_e32 v170, v100, v170
	v_mul_f32_e32 v173, v101, v173
	v_mul_f32_e32 v147, v147, v146
	v_mul_f32_e32 v166, v166, v149
	v_mul_f32_e32 v169, v169, v168
	v_mul_f32_e32 v172, v172, v171
	v_mul_f32_e32 v98, v147, v148
	v_mul_f32_e32 v99, v166, v167
	v_mul_f32_e32 v100, v169, v170
	v_mul_f32_e32 v101, v172, v173
	v_cvt_pk_bf16_f32 v192, v102, v103
	v_cvt_pk_bf16_f32 v193, v104, v105
	v_cvt_pk_bf16_f32 v194, v98, v99
	v_cvt_pk_bf16_f32 v195, v100, v101
	global_store_dwordx4 v[176:177], v[192:195], off offset:3328
	s_mov_b64 s[6:7], 0x10000
	v_lshl_add_u64 v[176:177], v[176:177], 0, s[6:7]
	global_load_dwordx4 v[188:191], v[174:175], off
	global_load_dwordx4 v[192:195], v[174:175], off offset:256
	global_load_dwordx4 v[196:199], v[178:179], off
	global_load_dwordx4 v[200:203], v[178:179], off offset:256
	s_mov_b64 s[6:7], 0x4000
	v_lshl_add_u64 v[174:175], v[174:175], 0, s[6:7]
	s_mov_b64 s[6:7], 0x8a000
	v_lshl_add_u64 v[178:179], v[178:179], 0, s[6:7]
	s_waitcnt vmcnt(12)
; __device__ __forceinline__ float sigmoidf_(float x) { return __builtin_amdgcn_rcpf(1.f + __expf(-x)); }
; __device__ __forceinline__ float siluf_(float x) { return x * sigmoidf_(x); }
;     __device__ __forceinline__ void operator()(AccT& acc, const Unit& u, int wr, int wc, int fr, int fq) const {
;     ...
;         for (int ai = 0; ai < 2; ++ai)
; #pragma unroll
;             for (int m = 0; m < 4; ++m) { const size_t row = (size_t)(row0 + ai * 128 + m * 16);
; #pragma unroll
;                 for (int bj = 0; bj < 2; ++bj) { const int c = col0 + bj * 128;
;                     float y8[8], z8[8], o8[8]; ld8(yd + row * 512 + c, y8); ld8(proj + row * NP + O_DZ + c, z8);
;                     const f32x4 b0 = *(const f32x4*)(gb + c), b1 = *(const f32x4*)(gb + c + 4);
; #pragma unroll
;                     for (int e = 0; e < 4; ++e) { o8[e] = y8[e] * sigmoidf_(acc[ai][bj][m][0][e] + b0[e]) * siluf_(z8[e]); o8[4 + e] = y8[4 + e] * sigmoidf_(acc[ai][bj][m][1][e] + b1[e]) * siluf_(z8[4 + e]); }
;                     st8(ys + row * DM + 1536 + c, o8); } }
	v_add_f32_e32 v94, v94, v222
	v_add_f32_e32 v95, v95, v223
	v_add_f32_e32 v96, v96, v224
	v_add_f32_e32 v97, v97, v225
	v_lshlrev_b32_e32 v146, 16, v216
	v_and_b32_e32 v149, 0xffff0000, v216
	v_lshlrev_b32_e32 v168, 16, v217
	v_and_b32_e32 v171, 0xffff0000, v217
	v_mul_f32_e32 v94, 0xbfb8aa3b, v94
	v_mul_f32_e32 v95, 0xbfb8aa3b, v95
	v_mul_f32_e32 v96, 0xbfb8aa3b, v96
	v_mul_f32_e32 v97, 0xbfb8aa3b, v97
	v_mul_f32_e32 v147, 0xbfb8aa3b, v146
	v_mul_f32_e32 v166, 0xbfb8aa3b, v149
	v_mul_f32_e32 v169, 0xbfb8aa3b, v168
	v_mul_f32_e32 v172, 0xbfb8aa3b, v171
	v_exp_f32_e32 v94, v94
	v_exp_f32_e32 v95, v95
	v_exp_f32_e32 v96, v96
	v_exp_f32_e32 v97, v97
	v_exp_f32_e32 v147, v147
	v_exp_f32_e32 v166, v166
	v_exp_f32_e32 v169, v169
	v_exp_f32_e32 v172, v172
	v_lshlrev_b32_e32 v148, 16, v208
	v_and_b32_e32 v167, 0xffff0000, v208
	v_lshlrev_b32_e32 v170, 16, v209
	v_and_b32_e32 v173, 0xffff0000, v209
	v_add_f32_e32 v94, 1.0, v94
	v_add_f32_e32 v95, 1.0, v95
	v_add_f32_e32 v96, 1.0, v96
	v_add_f32_e32 v97, 1.0, v97
	v_add_f32_e32 v147, 1.0, v147
	v_add_f32_e32 v166, 1.0, v166
	v_add_f32_e32 v169, 1.0, v169
	v_add_f32_e32 v172, 1.0, v172
	v_rcp_f32_e32 v94, v94
	v_rcp_f32_e32 v95, v95
	v_rcp_f32_e32 v96, v96
	v_rcp_f32_e32 v97, v97
	v_rcp_f32_e32 v147, v147
	v_rcp_f32_e32 v166, v166
	v_rcp_f32_e32 v169, v169
	v_rcp_f32_e32 v172, v172
	v_mul_f32_e32 v148, v94, v148
	v_mul_f32_e32 v167, v95, v167
	v_mul_f32_e32 v170, v96, v170
	v_mul_f32_e32 v173, v97, v173
	v_mul_f32_e32 v147, v147, v146
	v_mul_f32_e32 v166, v166, v149
	v_mul_f32_e32 v169, v169, v168
	v_mul_f32_e32 v172, v172, v171
	v_mul_f32_e32 v94, v147, v148
	v_mul_f32_e32 v95, v166, v167
	v_mul_f32_e32 v96, v169, v170
	v_mul_f32_e32 v97, v172, v173
	v_add_f32_e32 v90, v90, v226
	v_add_f32_e32 v91, v91, v227
	v_add_f32_e32 v92, v92, v228
	v_add_f32_e32 v93, v93, v229
	v_lshlrev_b32_e32 v146, 16, v218
	v_and_b32_e32 v149, 0xffff0000, v218
	v_lshlrev_b32_e32 v168, 16, v219
	v_and_b32_e32 v171, 0xffff0000, v219
	v_mul_f32_e32 v90, 0xbfb8aa3b, v90
	v_mul_f32_e32 v91, 0xbfb8aa3b, v91
	v_mul_f32_e32 v92, 0xbfb8aa3b, v92
	v_mul_f32_e32 v93, 0xbfb8aa3b, v93
	v_mul_f32_e32 v147, 0xbfb8aa3b, v146
	v_mul_f32_e32 v166, 0xbfb8aa3b, v149
	v_mul_f32_e32 v169, 0xbfb8aa3b, v168
	v_mul_f32_e32 v172, 0xbfb8aa3b, v171
	v_exp_f32_e32 v90, v90
	v_exp_f32_e32 v91, v91
	v_exp_f32_e32 v92, v92
	v_exp_f32_e32 v93, v93
	v_exp_f32_e32 v147, v147
	v_exp_f32_e32 v166, v166
	v_exp_f32_e32 v169, v169
	v_exp_f32_e32 v172, v172
	v_lshlrev_b32_e32 v148, 16, v210
	v_and_b32_e32 v167, 0xffff0000, v210
	v_lshlrev_b32_e32 v170, 16, v211
	v_and_b32_e32 v173, 0xffff0000, v211
	v_add_f32_e32 v90, 1.0, v90
	v_add_f32_e32 v91, 1.0, v91
	v_add_f32_e32 v92, 1.0, v92
	v_add_f32_e32 v93, 1.0, v93
	v_add_f32_e32 v147, 1.0, v147
	v_add_f32_e32 v166, 1.0, v166
	v_add_f32_e32 v169, 1.0, v169
	v_add_f32_e32 v172, 1.0, v172
	v_rcp_f32_e32 v90, v90
	v_rcp_f32_e32 v91, v91
	v_rcp_f32_e32 v92, v92
	v_rcp_f32_e32 v93, v93
	v_rcp_f32_e32 v147, v147
	v_rcp_f32_e32 v166, v166
	v_rcp_f32_e32 v169, v169
	v_rcp_f32_e32 v172, v172
	v_mul_f32_e32 v148, v90, v148
	v_mul_f32_e32 v167, v91, v167
	v_mul_f32_e32 v170, v92, v170
	v_mul_f32_e32 v173, v93, v173
	v_mul_f32_e32 v147, v147, v146
	v_mul_f32_e32 v166, v166, v149
	v_mul_f32_e32 v169, v169, v168
	v_mul_f32_e32 v172, v172, v171
	v_mul_f32_e32 v90, v147, v148
	v_mul_f32_e32 v91, v166, v167
	v_mul_f32_e32 v92, v169, v170
	v_mul_f32_e32 v93, v172, v173
	v_cvt_pk_bf16_f32 v208, v94, v95
	v_cvt_pk_bf16_f32 v209, v96, v97
	v_cvt_pk_bf16_f32 v210, v90, v91
	v_cvt_pk_bf16_f32 v211, v92, v93
	global_store_dwordx4 v[176:177], v[208:211], off offset:3072
	v_add_f32_e32 v86, v86, v230
	v_add_f32_e32 v87, v87, v231
	v_add_f32_e32 v88, v88, v232
	v_add_f32_e32 v89, v89, v233
	v_lshlrev_b32_e32 v146, 16, v150
	v_and_b32_e32 v149, 0xffff0000, v150
	v_lshlrev_b32_e32 v168, 16, v151
	v_and_b32_e32 v171, 0xffff0000, v151
	v_mul_f32_e32 v86, 0xbfb8aa3b, v86
	v_mul_f32_e32 v87, 0xbfb8aa3b, v87
	v_mul_f32_e32 v88, 0xbfb8aa3b, v88
	v_mul_f32_e32 v89, 0xbfb8aa3b, v89
	v_mul_f32_e32 v147, 0xbfb8aa3b, v146
	v_mul_f32_e32 v166, 0xbfb8aa3b, v149
	v_mul_f32_e32 v169, 0xbfb8aa3b, v168
	v_mul_f32_e32 v172, 0xbfb8aa3b, v171
	v_exp_f32_e32 v86, v86
	v_exp_f32_e32 v87, v87
	v_exp_f32_e32 v88, v88
	v_exp_f32_e32 v89, v89
	v_exp_f32_e32 v147, v147
	v_exp_f32_e32 v166, v166
	v_exp_f32_e32 v169, v169
	v_exp_f32_e32 v172, v172
	v_lshlrev_b32_e32 v148, 16, v212
	v_and_b32_e32 v167, 0xffff0000, v212
	v_lshlrev_b32_e32 v170, 16, v213
	v_and_b32_e32 v173, 0xffff0000, v213
	v_add_f32_e32 v86, 1.0, v86
	v_add_f32_e32 v87, 1.0, v87
	v_add_f32_e32 v88, 1.0, v88
	v_add_f32_e32 v89, 1.0, v89
	v_add_f32_e32 v147, 1.0, v147
	v_add_f32_e32 v166, 1.0, v166
	v_add_f32_e32 v169, 1.0, v169
	v_add_f32_e32 v172, 1.0, v172
	v_rcp_f32_e32 v86, v86
	v_rcp_f32_e32 v87, v87
	v_rcp_f32_e32 v88, v88
	v_rcp_f32_e32 v89, v89
	v_rcp_f32_e32 v147, v147
	v_rcp_f32_e32 v166, v166
	v_rcp_f32_e32 v169, v169
	v_rcp_f32_e32 v172, v172
	v_mul_f32_e32 v148, v86, v148
	v_mul_f32_e32 v167, v87, v167
	v_mul_f32_e32 v170, v88, v170
	v_mul_f32_e32 v173, v89, v173
	v_mul_f32_e32 v147, v147, v146
	v_mul_f32_e32 v166, v166, v149
	v_mul_f32_e32 v169, v169, v168
	v_mul_f32_e32 v172, v172, v171
	v_mul_f32_e32 v86, v147, v148
	v_mul_f32_e32 v87, v166, v167
	v_mul_f32_e32 v88, v169, v170
	v_mul_f32_e32 v89, v172, v173
	v_add_f32_e32 v82, v82, v234
	v_add_f32_e32 v83, v83, v235
	v_add_f32_e32 v84, v84, v236
	v_add_f32_e32 v85, v85, v237
	v_lshlrev_b32_e32 v146, 16, v152
	v_and_b32_e32 v149, 0xffff0000, v152
	v_lshlrev_b32_e32 v168, 16, v153
	v_and_b32_e32 v171, 0xffff0000, v153
; __device__ __forceinline__ float sigmoidf_(float x) { return __builtin_amdgcn_rcpf(1.f + __expf(-x)); }
; __device__ __forceinline__ float siluf_(float x) { return x * sigmoidf_(x); }
;     __device__ __forceinline__ void operator()(AccT& acc, const Unit& u, int wr, int wc, int fr, int fq) const {
;     ...
;         for (int ai = 0; ai < 2; ++ai)
; #pragma unroll
;             for (int m = 0; m < 4; ++m) { const size_t row = (size_t)(row0 + ai * 128 + m * 16);
; #pragma unroll
;                 for (int bj = 0; bj < 2; ++bj) { const int c = col0 + bj * 128;
;                     float y8[8], z8[8], o8[8]; ld8(yd + row * 512 + c, y8); ld8(proj + row * NP + O_DZ + c, z8);
;                     const f32x4 b0 = *(const f32x4*)(gb + c), b1 = *(const f32x4*)(gb + c + 4);
; #pragma unroll
;                     for (int e = 0; e < 4; ++e) { o8[e] = y8[e] * sigmoidf_(acc[ai][bj][m][0][e] + b0[e]) * siluf_(z8[e]); o8[4 + e] = y8[4 + e] * sigmoidf_(acc[ai][bj][m][1][e] + b1[e]) * siluf_(z8[4 + e]); }
;                     st8(ys + row * DM + 1536 + c, o8); } }
	v_mul_f32_e32 v82, 0xbfb8aa3b, v82
	v_mul_f32_e32 v83, 0xbfb8aa3b, v83
	v_mul_f32_e32 v84, 0xbfb8aa3b, v84
	v_mul_f32_e32 v85, 0xbfb8aa3b, v85
	v_mul_f32_e32 v147, 0xbfb8aa3b, v146
	v_mul_f32_e32 v166, 0xbfb8aa3b, v149
	v_mul_f32_e32 v169, 0xbfb8aa3b, v168
	v_mul_f32_e32 v172, 0xbfb8aa3b, v171
	v_exp_f32_e32 v82, v82
	v_exp_f32_e32 v83, v83
	v_exp_f32_e32 v84, v84
	v_exp_f32_e32 v85, v85
	v_exp_f32_e32 v147, v147
	v_exp_f32_e32 v166, v166
	v_exp_f32_e32 v169, v169
	v_exp_f32_e32 v172, v172
	v_lshlrev_b32_e32 v148, 16, v214
	v_and_b32_e32 v167, 0xffff0000, v214
	v_lshlrev_b32_e32 v170, 16, v215
	v_and_b32_e32 v173, 0xffff0000, v215
	v_add_f32_e32 v82, 1.0, v82
	v_add_f32_e32 v83, 1.0, v83
	v_add_f32_e32 v84, 1.0, v84
	v_add_f32_e32 v85, 1.0, v85
	v_add_f32_e32 v147, 1.0, v147
	v_add_f32_e32 v166, 1.0, v166
	v_add_f32_e32 v169, 1.0, v169
	v_add_f32_e32 v172, 1.0, v172
	v_rcp_f32_e32 v82, v82
	v_rcp_f32_e32 v83, v83
	v_rcp_f32_e32 v84, v84
	v_rcp_f32_e32 v85, v85
	v_rcp_f32_e32 v147, v147
	v_rcp_f32_e32 v166, v166
	v_rcp_f32_e32 v169, v169
	v_rcp_f32_e32 v172, v172
	v_mul_f32_e32 v148, v82, v148
	v_mul_f32_e32 v167, v83, v167
	v_mul_f32_e32 v170, v84, v170
	v_mul_f32_e32 v173, v85, v173
	v_mul_f32_e32 v147, v147, v146
	v_mul_f32_e32 v166, v166, v149
	v_mul_f32_e32 v169, v169, v168
	v_mul_f32_e32 v172, v172, v171
	v_mul_f32_e32 v82, v147, v148
	v_mul_f32_e32 v83, v166, v167
	v_mul_f32_e32 v84, v169, v170
	v_mul_f32_e32 v85, v172, v173
	v_cvt_pk_bf16_f32 v212, v86, v87
	v_cvt_pk_bf16_f32 v213, v88, v89
	v_cvt_pk_bf16_f32 v214, v82, v83
	v_cvt_pk_bf16_f32 v215, v84, v85
	global_store_dwordx4 v[176:177], v[212:215], off offset:3328
	s_mov_b64 s[6:7], 0x10000
	v_lshl_add_u64 v[176:177], v[176:177], 0, s[6:7]
	global_load_dwordx4 v[208:211], v[174:175], off
	global_load_dwordx4 v[212:215], v[174:175], off offset:256
	global_load_dwordx4 v[216:219], v[178:179], off
	global_load_dwordx4 v[150:153], v[178:179], off offset:256
	s_mov_b64 s[6:7], 0x4000
	v_lshl_add_u64 v[174:175], v[174:175], 0, s[6:7]
	s_mov_b64 s[6:7], 0x8a000
	v_lshl_add_u64 v[178:179], v[178:179], 0, s[6:7]
	s_waitcnt vmcnt(12)
	v_add_f32_e32 v78, v78, v222
	v_add_f32_e32 v79, v79, v223
	v_add_f32_e32 v80, v80, v224
	v_add_f32_e32 v81, v81, v225
	v_lshlrev_b32_e32 v146, 16, v138
	v_and_b32_e32 v149, 0xffff0000, v138
	v_lshlrev_b32_e32 v168, 16, v139
	v_and_b32_e32 v171, 0xffff0000, v139
	v_mul_f32_e32 v78, 0xbfb8aa3b, v78
	v_mul_f32_e32 v79, 0xbfb8aa3b, v79
	v_mul_f32_e32 v80, 0xbfb8aa3b, v80
	v_mul_f32_e32 v81, 0xbfb8aa3b, v81
	v_mul_f32_e32 v147, 0xbfb8aa3b, v146
	v_mul_f32_e32 v166, 0xbfb8aa3b, v149
	v_mul_f32_e32 v169, 0xbfb8aa3b, v168
	v_mul_f32_e32 v172, 0xbfb8aa3b, v171
	v_exp_f32_e32 v78, v78
	v_exp_f32_e32 v79, v79
	v_exp_f32_e32 v80, v80
	v_exp_f32_e32 v81, v81
	v_exp_f32_e32 v147, v147
	v_exp_f32_e32 v166, v166
	v_exp_f32_e32 v169, v169
	v_exp_f32_e32 v172, v172
	v_lshlrev_b32_e32 v148, 16, v130
	v_and_b32_e32 v167, 0xffff0000, v130
	v_lshlrev_b32_e32 v170, 16, v131
	v_and_b32_e32 v173, 0xffff0000, v131
	v_add_f32_e32 v78, 1.0, v78
	v_add_f32_e32 v79, 1.0, v79
	v_add_f32_e32 v80, 1.0, v80
	v_add_f32_e32 v81, 1.0, v81
	v_add_f32_e32 v147, 1.0, v147
	v_add_f32_e32 v166, 1.0, v166
	v_add_f32_e32 v169, 1.0, v169
	v_add_f32_e32 v172, 1.0, v172
	v_rcp_f32_e32 v78, v78
	v_rcp_f32_e32 v79, v79
	v_rcp_f32_e32 v80, v80
	v_rcp_f32_e32 v81, v81
	v_rcp_f32_e32 v147, v147
	v_rcp_f32_e32 v166, v166
	v_rcp_f32_e32 v169, v169
	v_rcp_f32_e32 v172, v172
	v_mul_f32_e32 v148, v78, v148
	v_mul_f32_e32 v167, v79, v167
	v_mul_f32_e32 v170, v80, v170
	v_mul_f32_e32 v173, v81, v173
	v_mul_f32_e32 v147, v147, v146
	v_mul_f32_e32 v166, v166, v149
	v_mul_f32_e32 v169, v169, v168
	v_mul_f32_e32 v172, v172, v171
	v_mul_f32_e32 v78, v147, v148
	v_mul_f32_e32 v79, v166, v167
	v_mul_f32_e32 v80, v169, v170
	v_mul_f32_e32 v81, v172, v173
	v_add_f32_e32 v74, v74, v226
	v_add_f32_e32 v75, v75, v227
	v_add_f32_e32 v76, v76, v228
	v_add_f32_e32 v77, v77, v229
	v_lshlrev_b32_e32 v146, 16, v140
	v_and_b32_e32 v149, 0xffff0000, v140
	v_lshlrev_b32_e32 v168, 16, v141
	v_and_b32_e32 v171, 0xffff0000, v141
	v_mul_f32_e32 v74, 0xbfb8aa3b, v74
	v_mul_f32_e32 v75, 0xbfb8aa3b, v75
	v_mul_f32_e32 v76, 0xbfb8aa3b, v76
	v_mul_f32_e32 v77, 0xbfb8aa3b, v77
	v_mul_f32_e32 v147, 0xbfb8aa3b, v146
	v_mul_f32_e32 v166, 0xbfb8aa3b, v149
	v_mul_f32_e32 v169, 0xbfb8aa3b, v168
	v_mul_f32_e32 v172, 0xbfb8aa3b, v171
	v_exp_f32_e32 v74, v74
	v_exp_f32_e32 v75, v75
	v_exp_f32_e32 v76, v76
	v_exp_f32_e32 v77, v77
	v_exp_f32_e32 v147, v147
	v_exp_f32_e32 v166, v166
	v_exp_f32_e32 v169, v169
	v_exp_f32_e32 v172, v172
	v_lshlrev_b32_e32 v148, 16, v132
	v_and_b32_e32 v167, 0xffff0000, v132
	v_lshlrev_b32_e32 v170, 16, v133
	v_and_b32_e32 v173, 0xffff0000, v133
	v_add_f32_e32 v74, 1.0, v74
	v_add_f32_e32 v75, 1.0, v75
	v_add_f32_e32 v76, 1.0, v76
	v_add_f32_e32 v77, 1.0, v77
	v_add_f32_e32 v147, 1.0, v147
	v_add_f32_e32 v166, 1.0, v166
	v_add_f32_e32 v169, 1.0, v169
	v_add_f32_e32 v172, 1.0, v172
	v_rcp_f32_e32 v74, v74
	v_rcp_f32_e32 v75, v75
	v_rcp_f32_e32 v76, v76
	v_rcp_f32_e32 v77, v77
	v_rcp_f32_e32 v147, v147
	v_rcp_f32_e32 v166, v166
	v_rcp_f32_e32 v169, v169
	v_rcp_f32_e32 v172, v172
	v_mul_f32_e32 v148, v74, v148
	v_mul_f32_e32 v167, v75, v167
	v_mul_f32_e32 v170, v76, v170
	v_mul_f32_e32 v173, v77, v173
	v_mul_f32_e32 v147, v147, v146
	v_mul_f32_e32 v166, v166, v149
	v_mul_f32_e32 v169, v169, v168
	v_mul_f32_e32 v172, v172, v171
	v_mul_f32_e32 v74, v147, v148
	v_mul_f32_e32 v75, v166, v167
	v_mul_f32_e32 v76, v169, v170
	v_mul_f32_e32 v77, v172, v173
	v_cvt_pk_bf16_f32 v130, v78, v79
	v_cvt_pk_bf16_f32 v131, v80, v81
; __device__ __forceinline__ float sigmoidf_(float x) { return __builtin_amdgcn_rcpf(1.f + __expf(-x)); }
; __device__ __forceinline__ float siluf_(float x) { return x * sigmoidf_(x); }
;     __device__ __forceinline__ void operator()(AccT& acc, const Unit& u, int wr, int wc, int fr, int fq) const {
;     ...
;         for (int ai = 0; ai < 2; ++ai)
; #pragma unroll
;             for (int m = 0; m < 4; ++m) { const size_t row = (size_t)(row0 + ai * 128 + m * 16);
; #pragma unroll
;                 for (int bj = 0; bj < 2; ++bj) { const int c = col0 + bj * 128;
;                     float y8[8], z8[8], o8[8]; ld8(yd + row * 512 + c, y8); ld8(proj + row * NP + O_DZ + c, z8);
;                     const f32x4 b0 = *(const f32x4*)(gb + c), b1 = *(const f32x4*)(gb + c + 4);
; #pragma unroll
;                     for (int e = 0; e < 4; ++e) { o8[e] = y8[e] * sigmoidf_(acc[ai][bj][m][0][e] + b0[e]) * siluf_(z8[e]); o8[4 + e] = y8[4 + e] * sigmoidf_(acc[ai][bj][m][1][e] + b1[e]) * siluf_(z8[4 + e]); }
;                     st8(ys + row * DM + 1536 + c, o8); } }
	v_cvt_pk_bf16_f32 v132, v74, v75
	v_cvt_pk_bf16_f32 v133, v76, v77
	global_store_dwordx4 v[176:177], v[130:133], off offset:3072
	v_add_f32_e32 v70, v70, v230
	v_add_f32_e32 v71, v71, v231
	v_add_f32_e32 v72, v72, v232
	v_add_f32_e32 v73, v73, v233
	v_lshlrev_b32_e32 v146, 16, v142
	v_and_b32_e32 v149, 0xffff0000, v142
	v_lshlrev_b32_e32 v168, 16, v143
	v_and_b32_e32 v171, 0xffff0000, v143
	v_mul_f32_e32 v70, 0xbfb8aa3b, v70
	v_mul_f32_e32 v71, 0xbfb8aa3b, v71
	v_mul_f32_e32 v72, 0xbfb8aa3b, v72
	v_mul_f32_e32 v73, 0xbfb8aa3b, v73
	v_mul_f32_e32 v147, 0xbfb8aa3b, v146
	v_mul_f32_e32 v166, 0xbfb8aa3b, v149
	v_mul_f32_e32 v169, 0xbfb8aa3b, v168
	v_mul_f32_e32 v172, 0xbfb8aa3b, v171
	v_exp_f32_e32 v70, v70
	v_exp_f32_e32 v71, v71
	v_exp_f32_e32 v72, v72
	v_exp_f32_e32 v73, v73
	v_exp_f32_e32 v147, v147
	v_exp_f32_e32 v166, v166
	v_exp_f32_e32 v169, v169
	v_exp_f32_e32 v172, v172
	v_lshlrev_b32_e32 v148, 16, v134
	v_and_b32_e32 v167, 0xffff0000, v134
	v_lshlrev_b32_e32 v170, 16, v135
	v_and_b32_e32 v173, 0xffff0000, v135
	v_add_f32_e32 v70, 1.0, v70
	v_add_f32_e32 v71, 1.0, v71
	v_add_f32_e32 v72, 1.0, v72
	v_add_f32_e32 v73, 1.0, v73
	v_add_f32_e32 v147, 1.0, v147
	v_add_f32_e32 v166, 1.0, v166
	v_add_f32_e32 v169, 1.0, v169
	v_add_f32_e32 v172, 1.0, v172
	v_rcp_f32_e32 v70, v70
	v_rcp_f32_e32 v71, v71
	v_rcp_f32_e32 v72, v72
	v_rcp_f32_e32 v73, v73
	v_rcp_f32_e32 v147, v147
	v_rcp_f32_e32 v166, v166
	v_rcp_f32_e32 v169, v169
	v_rcp_f32_e32 v172, v172
	v_mul_f32_e32 v148, v70, v148
	v_mul_f32_e32 v167, v71, v167
	v_mul_f32_e32 v170, v72, v170
	v_mul_f32_e32 v173, v73, v173
	v_mul_f32_e32 v147, v147, v146
	v_mul_f32_e32 v166, v166, v149
	v_mul_f32_e32 v169, v169, v168
	v_mul_f32_e32 v172, v172, v171
	v_mul_f32_e32 v70, v147, v148
	v_mul_f32_e32 v71, v166, v167
	v_mul_f32_e32 v72, v169, v170
	v_mul_f32_e32 v73, v172, v173
	v_add_f32_e32 v66, v66, v234
	v_add_f32_e32 v67, v67, v235
	v_add_f32_e32 v68, v68, v236
	v_add_f32_e32 v69, v69, v237
	v_lshlrev_b32_e32 v146, 16, v144
	v_and_b32_e32 v149, 0xffff0000, v144
	v_lshlrev_b32_e32 v168, 16, v145
	v_and_b32_e32 v171, 0xffff0000, v145
	v_mul_f32_e32 v66, 0xbfb8aa3b, v66
	v_mul_f32_e32 v67, 0xbfb8aa3b, v67
	v_mul_f32_e32 v68, 0xbfb8aa3b, v68
	v_mul_f32_e32 v69, 0xbfb8aa3b, v69
	v_mul_f32_e32 v147, 0xbfb8aa3b, v146
	v_mul_f32_e32 v166, 0xbfb8aa3b, v149
	v_mul_f32_e32 v169, 0xbfb8aa3b, v168
	v_mul_f32_e32 v172, 0xbfb8aa3b, v171
	v_exp_f32_e32 v66, v66
	v_exp_f32_e32 v67, v67
	v_exp_f32_e32 v68, v68
	v_exp_f32_e32 v69, v69
	v_exp_f32_e32 v147, v147
	v_exp_f32_e32 v166, v166
	v_exp_f32_e32 v169, v169
	v_exp_f32_e32 v172, v172
	v_lshlrev_b32_e32 v148, 16, v136
	v_and_b32_e32 v167, 0xffff0000, v136
	v_lshlrev_b32_e32 v170, 16, v137
	v_and_b32_e32 v173, 0xffff0000, v137
	v_add_f32_e32 v66, 1.0, v66
	v_add_f32_e32 v67, 1.0, v67
	v_add_f32_e32 v68, 1.0, v68
	v_add_f32_e32 v69, 1.0, v69
	v_add_f32_e32 v147, 1.0, v147
	v_add_f32_e32 v166, 1.0, v166
	v_add_f32_e32 v169, 1.0, v169
	v_add_f32_e32 v172, 1.0, v172
	v_rcp_f32_e32 v66, v66
	v_rcp_f32_e32 v67, v67
	v_rcp_f32_e32 v68, v68
	v_rcp_f32_e32 v69, v69
	v_rcp_f32_e32 v147, v147
	v_rcp_f32_e32 v166, v166
	v_rcp_f32_e32 v169, v169
	v_rcp_f32_e32 v172, v172
	v_mul_f32_e32 v148, v66, v148
	v_mul_f32_e32 v167, v67, v167
	v_mul_f32_e32 v170, v68, v170
	v_mul_f32_e32 v173, v69, v173
	v_mul_f32_e32 v147, v147, v146
	v_mul_f32_e32 v166, v166, v149
	v_mul_f32_e32 v169, v169, v168
	v_mul_f32_e32 v172, v172, v171
	v_mul_f32_e32 v66, v147, v148
	v_mul_f32_e32 v67, v166, v167
	v_mul_f32_e32 v68, v169, v170
	v_mul_f32_e32 v69, v172, v173
	v_cvt_pk_bf16_f32 v134, v70, v71
	v_cvt_pk_bf16_f32 v135, v72, v73
	v_cvt_pk_bf16_f32 v136, v66, v67
	v_cvt_pk_bf16_f32 v137, v68, v69
	global_store_dwordx4 v[176:177], v[134:137], off offset:3328
	s_mov_b64 s[6:7], 0x50000
	v_lshl_add_u64 v[176:177], v[176:177], 0, s[6:7]
	global_load_dwordx4 v[130:133], v[174:175], off
	global_load_dwordx4 v[134:137], v[174:175], off offset:256
	global_load_dwordx4 v[138:141], v[178:179], off
	global_load_dwordx4 v[142:145], v[178:179], off offset:256
	s_mov_b64 s[6:7], 0x4000
	v_lshl_add_u64 v[174:175], v[174:175], 0, s[6:7]
	s_mov_b64 s[6:7], 0x8a000
	v_lshl_add_u64 v[178:179], v[178:179], 0, s[6:7]
	s_waitcnt vmcnt(12)
; __device__ __forceinline__ float sigmoidf_(float x) { return __builtin_amdgcn_rcpf(1.f + __expf(-x)); }
; __device__ __forceinline__ float siluf_(float x) { return x * sigmoidf_(x); }
;     __device__ __forceinline__ void operator()(AccT& acc, const Unit& u, int wr, int wc, int fr, int fq) const {
;     ...
;         for (int ai = 0; ai < 2; ++ai)
; #pragma unroll
;             for (int m = 0; m < 4; ++m) { const size_t row = (size_t)(row0 + ai * 128 + m * 16);
; #pragma unroll
;                 for (int bj = 0; bj < 2; ++bj) { const int c = col0 + bj * 128;
;                     float y8[8], z8[8], o8[8]; ld8(yd + row * 512 + c, y8); ld8(proj + row * NP + O_DZ + c, z8);
;                     const f32x4 b0 = *(const f32x4*)(gb + c), b1 = *(const f32x4*)(gb + c + 4);
; #pragma unroll
;                     for (int e = 0; e < 4; ++e) { o8[e] = y8[e] * sigmoidf_(acc[ai][bj][m][0][e] + b0[e]) * siluf_(z8[e]); o8[4 + e] = y8[4 + e] * sigmoidf_(acc[ai][bj][m][1][e] + b1[e]) * siluf_(z8[4 + e]); }
;                     st8(ys + row * DM + 1536 + c, o8); } }
	v_add_f32_e32 v62, v62, v222
	v_add_f32_e32 v63, v63, v223
	v_add_f32_e32 v64, v64, v224
	v_add_f32_e32 v65, v65, v225
	v_lshlrev_b32_e32 v146, 16, v196
	v_and_b32_e32 v149, 0xffff0000, v196
	v_lshlrev_b32_e32 v168, 16, v197
	v_and_b32_e32 v171, 0xffff0000, v197
	v_mul_f32_e32 v62, 0xbfb8aa3b, v62
	v_mul_f32_e32 v63, 0xbfb8aa3b, v63
	v_mul_f32_e32 v64, 0xbfb8aa3b, v64
	v_mul_f32_e32 v65, 0xbfb8aa3b, v65
	v_mul_f32_e32 v147, 0xbfb8aa3b, v146
	v_mul_f32_e32 v166, 0xbfb8aa3b, v149
	v_mul_f32_e32 v169, 0xbfb8aa3b, v168
	v_mul_f32_e32 v172, 0xbfb8aa3b, v171
	v_exp_f32_e32 v62, v62
	v_exp_f32_e32 v63, v63
	v_exp_f32_e32 v64, v64
	v_exp_f32_e32 v65, v65
	v_exp_f32_e32 v147, v147
	v_exp_f32_e32 v166, v166
	v_exp_f32_e32 v169, v169
	v_exp_f32_e32 v172, v172
	v_lshlrev_b32_e32 v148, 16, v188
	v_and_b32_e32 v167, 0xffff0000, v188
	v_lshlrev_b32_e32 v170, 16, v189
	v_and_b32_e32 v173, 0xffff0000, v189
	v_add_f32_e32 v62, 1.0, v62
	v_add_f32_e32 v63, 1.0, v63
	v_add_f32_e32 v64, 1.0, v64
	v_add_f32_e32 v65, 1.0, v65
	v_add_f32_e32 v147, 1.0, v147
	v_add_f32_e32 v166, 1.0, v166
	v_add_f32_e32 v169, 1.0, v169
	v_add_f32_e32 v172, 1.0, v172
	v_rcp_f32_e32 v62, v62
	v_rcp_f32_e32 v63, v63
	v_rcp_f32_e32 v64, v64
	v_rcp_f32_e32 v65, v65
	v_rcp_f32_e32 v147, v147
	v_rcp_f32_e32 v166, v166
	v_rcp_f32_e32 v169, v169
	v_rcp_f32_e32 v172, v172
	v_mul_f32_e32 v148, v62, v148
	v_mul_f32_e32 v167, v63, v167
	v_mul_f32_e32 v170, v64, v170
	v_mul_f32_e32 v173, v65, v173
	v_mul_f32_e32 v147, v147, v146
	v_mul_f32_e32 v166, v166, v149
	v_mul_f32_e32 v169, v169, v168
	v_mul_f32_e32 v172, v172, v171
	v_mul_f32_e32 v62, v147, v148
	v_mul_f32_e32 v63, v166, v167
	v_mul_f32_e32 v64, v169, v170
	v_mul_f32_e32 v65, v172, v173
	v_add_f32_e32 v58, v58, v226
	v_add_f32_e32 v59, v59, v227
	v_add_f32_e32 v60, v60, v228
	v_add_f32_e32 v61, v61, v229
	v_lshlrev_b32_e32 v146, 16, v198
	v_and_b32_e32 v149, 0xffff0000, v198
	v_lshlrev_b32_e32 v168, 16, v199
	v_and_b32_e32 v171, 0xffff0000, v199
	v_mul_f32_e32 v58, 0xbfb8aa3b, v58
	v_mul_f32_e32 v59, 0xbfb8aa3b, v59
	v_mul_f32_e32 v60, 0xbfb8aa3b, v60
	v_mul_f32_e32 v61, 0xbfb8aa3b, v61
	v_mul_f32_e32 v147, 0xbfb8aa3b, v146
	v_mul_f32_e32 v166, 0xbfb8aa3b, v149
	v_mul_f32_e32 v169, 0xbfb8aa3b, v168
	v_mul_f32_e32 v172, 0xbfb8aa3b, v171
	v_exp_f32_e32 v58, v58
	v_exp_f32_e32 v59, v59
	v_exp_f32_e32 v60, v60
	v_exp_f32_e32 v61, v61
	v_exp_f32_e32 v147, v147
	v_exp_f32_e32 v166, v166
	v_exp_f32_e32 v169, v169
	v_exp_f32_e32 v172, v172
	v_lshlrev_b32_e32 v148, 16, v190
	v_and_b32_e32 v167, 0xffff0000, v190
	v_lshlrev_b32_e32 v170, 16, v191
	v_and_b32_e32 v173, 0xffff0000, v191
	v_add_f32_e32 v58, 1.0, v58
	v_add_f32_e32 v59, 1.0, v59
	v_add_f32_e32 v60, 1.0, v60
	v_add_f32_e32 v61, 1.0, v61
	v_add_f32_e32 v147, 1.0, v147
	v_add_f32_e32 v166, 1.0, v166
	v_add_f32_e32 v169, 1.0, v169
	v_add_f32_e32 v172, 1.0, v172
	v_rcp_f32_e32 v58, v58
	v_rcp_f32_e32 v59, v59
	v_rcp_f32_e32 v60, v60
	v_rcp_f32_e32 v61, v61
	v_rcp_f32_e32 v147, v147
	v_rcp_f32_e32 v166, v166
	v_rcp_f32_e32 v169, v169
	v_rcp_f32_e32 v172, v172
	v_mul_f32_e32 v148, v58, v148
	v_mul_f32_e32 v167, v59, v167
	v_mul_f32_e32 v170, v60, v170
	v_mul_f32_e32 v173, v61, v173
	v_mul_f32_e32 v147, v147, v146
	v_mul_f32_e32 v166, v166, v149
	v_mul_f32_e32 v169, v169, v168
	v_mul_f32_e32 v172, v172, v171
	v_mul_f32_e32 v58, v147, v148
	v_mul_f32_e32 v59, v166, v167
	v_mul_f32_e32 v60, v169, v170
	v_mul_f32_e32 v61, v172, v173
	v_cvt_pk_bf16_f32 v188, v62, v63
	v_cvt_pk_bf16_f32 v189, v64, v65
	v_cvt_pk_bf16_f32 v190, v58, v59
	v_cvt_pk_bf16_f32 v191, v60, v61
	global_store_dwordx4 v[176:177], v[188:191], off offset:3072
	v_add_f32_e32 v54, v54, v230
	v_add_f32_e32 v55, v55, v231
	v_add_f32_e32 v56, v56, v232
	v_add_f32_e32 v57, v57, v233
	v_lshlrev_b32_e32 v146, 16, v200
	v_and_b32_e32 v149, 0xffff0000, v200
	v_lshlrev_b32_e32 v168, 16, v201
	v_and_b32_e32 v171, 0xffff0000, v201
	v_mul_f32_e32 v54, 0xbfb8aa3b, v54
	v_mul_f32_e32 v55, 0xbfb8aa3b, v55
	v_mul_f32_e32 v56, 0xbfb8aa3b, v56
	v_mul_f32_e32 v57, 0xbfb8aa3b, v57
	v_mul_f32_e32 v147, 0xbfb8aa3b, v146
	v_mul_f32_e32 v166, 0xbfb8aa3b, v149
	v_mul_f32_e32 v169, 0xbfb8aa3b, v168
	v_mul_f32_e32 v172, 0xbfb8aa3b, v171
	v_exp_f32_e32 v54, v54
	v_exp_f32_e32 v55, v55
	v_exp_f32_e32 v56, v56
	v_exp_f32_e32 v57, v57
	v_exp_f32_e32 v147, v147
	v_exp_f32_e32 v166, v166
	v_exp_f32_e32 v169, v169
	v_exp_f32_e32 v172, v172
	v_lshlrev_b32_e32 v148, 16, v192
	v_and_b32_e32 v167, 0xffff0000, v192
	v_lshlrev_b32_e32 v170, 16, v193
	v_and_b32_e32 v173, 0xffff0000, v193
	v_add_f32_e32 v54, 1.0, v54
	v_add_f32_e32 v55, 1.0, v55
	v_add_f32_e32 v56, 1.0, v56
	v_add_f32_e32 v57, 1.0, v57
	v_add_f32_e32 v147, 1.0, v147
	v_add_f32_e32 v166, 1.0, v166
	v_add_f32_e32 v169, 1.0, v169
	v_add_f32_e32 v172, 1.0, v172
	v_rcp_f32_e32 v54, v54
	v_rcp_f32_e32 v55, v55
	v_rcp_f32_e32 v56, v56
	v_rcp_f32_e32 v57, v57
	v_rcp_f32_e32 v147, v147
	v_rcp_f32_e32 v166, v166
	v_rcp_f32_e32 v169, v169
	v_rcp_f32_e32 v172, v172
	v_mul_f32_e32 v148, v54, v148
	v_mul_f32_e32 v167, v55, v167
	v_mul_f32_e32 v170, v56, v170
	v_mul_f32_e32 v173, v57, v173
	v_mul_f32_e32 v147, v147, v146
	v_mul_f32_e32 v166, v166, v149
	v_mul_f32_e32 v169, v169, v168
	v_mul_f32_e32 v172, v172, v171
	v_mul_f32_e32 v54, v147, v148
	v_mul_f32_e32 v55, v166, v167
	v_mul_f32_e32 v56, v169, v170
	v_mul_f32_e32 v57, v172, v173
	v_add_f32_e32 v50, v50, v234
	v_add_f32_e32 v51, v51, v235
	v_add_f32_e32 v52, v52, v236
	v_add_f32_e32 v53, v53, v237
	v_lshlrev_b32_e32 v146, 16, v202
	v_and_b32_e32 v149, 0xffff0000, v202
	v_lshlrev_b32_e32 v168, 16, v203
	v_and_b32_e32 v171, 0xffff0000, v203
; __device__ __forceinline__ float sigmoidf_(float x) { return __builtin_amdgcn_rcpf(1.f + __expf(-x)); }
; __device__ __forceinline__ float siluf_(float x) { return x * sigmoidf_(x); }
;     __device__ __forceinline__ void operator()(AccT& acc, const Unit& u, int wr, int wc, int fr, int fq) const {
;     ...
;         for (int ai = 0; ai < 2; ++ai)
; #pragma unroll
;             for (int m = 0; m < 4; ++m) { const size_t row = (size_t)(row0 + ai * 128 + m * 16);
; #pragma unroll
;                 for (int bj = 0; bj < 2; ++bj) { const int c = col0 + bj * 128;
;                     float y8[8], z8[8], o8[8]; ld8(yd + row * 512 + c, y8); ld8(proj + row * NP + O_DZ + c, z8);
;                     const f32x4 b0 = *(const f32x4*)(gb + c), b1 = *(const f32x4*)(gb + c + 4);
; #pragma unroll
;                     for (int e = 0; e < 4; ++e) { o8[e] = y8[e] * sigmoidf_(acc[ai][bj][m][0][e] + b0[e]) * siluf_(z8[e]); o8[4 + e] = y8[4 + e] * sigmoidf_(acc[ai][bj][m][1][e] + b1[e]) * siluf_(z8[4 + e]); }
;                     st8(ys + row * DM + 1536 + c, o8); } }
	v_mul_f32_e32 v50, 0xbfb8aa3b, v50
	v_mul_f32_e32 v51, 0xbfb8aa3b, v51
	v_mul_f32_e32 v52, 0xbfb8aa3b, v52
	v_mul_f32_e32 v53, 0xbfb8aa3b, v53
	v_mul_f32_e32 v147, 0xbfb8aa3b, v146
	v_mul_f32_e32 v166, 0xbfb8aa3b, v149
	v_mul_f32_e32 v169, 0xbfb8aa3b, v168
	v_mul_f32_e32 v172, 0xbfb8aa3b, v171
	v_exp_f32_e32 v50, v50
	v_exp_f32_e32 v51, v51
	v_exp_f32_e32 v52, v52
	v_exp_f32_e32 v53, v53
	v_exp_f32_e32 v147, v147
	v_exp_f32_e32 v166, v166
	v_exp_f32_e32 v169, v169
	v_exp_f32_e32 v172, v172
	v_lshlrev_b32_e32 v148, 16, v194
	v_and_b32_e32 v167, 0xffff0000, v194
	v_lshlrev_b32_e32 v170, 16, v195
	v_and_b32_e32 v173, 0xffff0000, v195
	v_add_f32_e32 v50, 1.0, v50
	v_add_f32_e32 v51, 1.0, v51
	v_add_f32_e32 v52, 1.0, v52
	v_add_f32_e32 v53, 1.0, v53
	v_add_f32_e32 v147, 1.0, v147
	v_add_f32_e32 v166, 1.0, v166
	v_add_f32_e32 v169, 1.0, v169
	v_add_f32_e32 v172, 1.0, v172
	v_rcp_f32_e32 v50, v50
	v_rcp_f32_e32 v51, v51
	v_rcp_f32_e32 v52, v52
	v_rcp_f32_e32 v53, v53
	v_rcp_f32_e32 v147, v147
	v_rcp_f32_e32 v166, v166
	v_rcp_f32_e32 v169, v169
	v_rcp_f32_e32 v172, v172
	v_mul_f32_e32 v148, v50, v148
	v_mul_f32_e32 v167, v51, v167
	v_mul_f32_e32 v170, v52, v170
	v_mul_f32_e32 v173, v53, v173
	v_mul_f32_e32 v147, v147, v146
	v_mul_f32_e32 v166, v166, v149
	v_mul_f32_e32 v169, v169, v168
	v_mul_f32_e32 v172, v172, v171
	v_mul_f32_e32 v50, v147, v148
	v_mul_f32_e32 v51, v166, v167
	v_mul_f32_e32 v52, v169, v170
	v_mul_f32_e32 v53, v172, v173
	v_cvt_pk_bf16_f32 v192, v54, v55
	v_cvt_pk_bf16_f32 v193, v56, v57
	v_cvt_pk_bf16_f32 v194, v50, v51
	v_cvt_pk_bf16_f32 v195, v52, v53
	global_store_dwordx4 v[176:177], v[192:195], off offset:3328
	s_mov_b64 s[6:7], 0x10000
	v_lshl_add_u64 v[176:177], v[176:177], 0, s[6:7]
	global_load_dwordx4 v[188:191], v[174:175], off
	global_load_dwordx4 v[192:195], v[174:175], off offset:256
	global_load_dwordx4 v[196:199], v[178:179], off
	global_load_dwordx4 v[200:203], v[178:179], off offset:256
	s_waitcnt vmcnt(12)
	v_add_f32_e32 v46, v46, v222
	v_add_f32_e32 v47, v47, v223
	v_add_f32_e32 v48, v48, v224
	v_add_f32_e32 v49, v49, v225
	v_lshlrev_b32_e32 v146, 16, v216
	v_and_b32_e32 v149, 0xffff0000, v216
	v_lshlrev_b32_e32 v168, 16, v217
	v_and_b32_e32 v171, 0xffff0000, v217
	v_mul_f32_e32 v46, 0xbfb8aa3b, v46
	v_mul_f32_e32 v47, 0xbfb8aa3b, v47
	v_mul_f32_e32 v48, 0xbfb8aa3b, v48
	v_mul_f32_e32 v49, 0xbfb8aa3b, v49
	v_mul_f32_e32 v147, 0xbfb8aa3b, v146
	v_mul_f32_e32 v166, 0xbfb8aa3b, v149
	v_mul_f32_e32 v169, 0xbfb8aa3b, v168
	v_mul_f32_e32 v172, 0xbfb8aa3b, v171
	v_exp_f32_e32 v46, v46
	v_exp_f32_e32 v47, v47
	v_exp_f32_e32 v48, v48
	v_exp_f32_e32 v49, v49
	v_exp_f32_e32 v147, v147
	v_exp_f32_e32 v166, v166
	v_exp_f32_e32 v169, v169
	v_exp_f32_e32 v172, v172
	v_lshlrev_b32_e32 v148, 16, v208
	v_and_b32_e32 v167, 0xffff0000, v208
	v_lshlrev_b32_e32 v170, 16, v209
	v_and_b32_e32 v173, 0xffff0000, v209
	v_add_f32_e32 v46, 1.0, v46
	v_add_f32_e32 v47, 1.0, v47
	v_add_f32_e32 v48, 1.0, v48
	v_add_f32_e32 v49, 1.0, v49
	v_add_f32_e32 v147, 1.0, v147
	v_add_f32_e32 v166, 1.0, v166
	v_add_f32_e32 v169, 1.0, v169
	v_add_f32_e32 v172, 1.0, v172
	v_rcp_f32_e32 v46, v46
	v_rcp_f32_e32 v47, v47
	v_rcp_f32_e32 v48, v48
	v_rcp_f32_e32 v49, v49
	v_rcp_f32_e32 v147, v147
	v_rcp_f32_e32 v166, v166
	v_rcp_f32_e32 v169, v169
	v_rcp_f32_e32 v172, v172
	v_mul_f32_e32 v148, v46, v148
	v_mul_f32_e32 v167, v47, v167
	v_mul_f32_e32 v170, v48, v170
	v_mul_f32_e32 v173, v49, v173
	v_mul_f32_e32 v147, v147, v146
	v_mul_f32_e32 v166, v166, v149
	v_mul_f32_e32 v169, v169, v168
	v_mul_f32_e32 v172, v172, v171
	v_mul_f32_e32 v46, v147, v148
	v_mul_f32_e32 v47, v166, v167
	v_mul_f32_e32 v48, v169, v170
	v_mul_f32_e32 v49, v172, v173
	v_add_f32_e32 v42, v42, v226
	v_add_f32_e32 v43, v43, v227
	v_add_f32_e32 v44, v44, v228
	v_add_f32_e32 v45, v45, v229
	v_lshlrev_b32_e32 v146, 16, v218
	v_and_b32_e32 v149, 0xffff0000, v218
	v_lshlrev_b32_e32 v168, 16, v219
	v_and_b32_e32 v171, 0xffff0000, v219
	v_mul_f32_e32 v42, 0xbfb8aa3b, v42
	v_mul_f32_e32 v43, 0xbfb8aa3b, v43
	v_mul_f32_e32 v44, 0xbfb8aa3b, v44
	v_mul_f32_e32 v45, 0xbfb8aa3b, v45
	v_mul_f32_e32 v147, 0xbfb8aa3b, v146
	v_mul_f32_e32 v166, 0xbfb8aa3b, v149
	v_mul_f32_e32 v169, 0xbfb8aa3b, v168
	v_mul_f32_e32 v172, 0xbfb8aa3b, v171
	v_exp_f32_e32 v42, v42
	v_exp_f32_e32 v43, v43
	v_exp_f32_e32 v44, v44
	v_exp_f32_e32 v45, v45
	v_exp_f32_e32 v147, v147
	v_exp_f32_e32 v166, v166
	v_exp_f32_e32 v169, v169
	v_exp_f32_e32 v172, v172
	v_lshlrev_b32_e32 v148, 16, v210
	v_and_b32_e32 v167, 0xffff0000, v210
	v_lshlrev_b32_e32 v170, 16, v211
	v_and_b32_e32 v173, 0xffff0000, v211
	v_add_f32_e32 v42, 1.0, v42
	v_add_f32_e32 v43, 1.0, v43
	v_add_f32_e32 v44, 1.0, v44
	v_add_f32_e32 v45, 1.0, v45
	v_add_f32_e32 v147, 1.0, v147
	v_add_f32_e32 v166, 1.0, v166
	v_add_f32_e32 v169, 1.0, v169
	v_add_f32_e32 v172, 1.0, v172
	v_rcp_f32_e32 v42, v42
	v_rcp_f32_e32 v43, v43
	v_rcp_f32_e32 v44, v44
	v_rcp_f32_e32 v45, v45
	v_rcp_f32_e32 v147, v147
	v_rcp_f32_e32 v166, v166
	v_rcp_f32_e32 v169, v169
	v_rcp_f32_e32 v172, v172
	v_mul_f32_e32 v148, v42, v148
	v_mul_f32_e32 v167, v43, v167
	v_mul_f32_e32 v170, v44, v170
	v_mul_f32_e32 v173, v45, v173
	v_mul_f32_e32 v147, v147, v146
	v_mul_f32_e32 v166, v166, v149
	v_mul_f32_e32 v169, v169, v168
	v_mul_f32_e32 v172, v172, v171
	v_mul_f32_e32 v42, v147, v148
	v_mul_f32_e32 v43, v166, v167
	v_mul_f32_e32 v44, v169, v170
	v_mul_f32_e32 v45, v172, v173
	v_cvt_pk_bf16_f32 v208, v46, v47
	v_cvt_pk_bf16_f32 v209, v48, v49
	v_cvt_pk_bf16_f32 v210, v42, v43
	v_cvt_pk_bf16_f32 v211, v44, v45
	global_store_dwordx4 v[176:177], v[208:211], off offset:3072
	v_add_f32_e32 v38, v38, v230
; __device__ __forceinline__ float sigmoidf_(float x) { return __builtin_amdgcn_rcpf(1.f + __expf(-x)); }
; __device__ __forceinline__ float siluf_(float x) { return x * sigmoidf_(x); }
;     __device__ __forceinline__ void operator()(AccT& acc, const Unit& u, int wr, int wc, int fr, int fq) const {
;     ...
;         for (int ai = 0; ai < 2; ++ai)
; #pragma unroll
;             for (int m = 0; m < 4; ++m) { const size_t row = (size_t)(row0 + ai * 128 + m * 16);
; #pragma unroll
;                 for (int bj = 0; bj < 2; ++bj) { const int c = col0 + bj * 128;
;                     float y8[8], z8[8], o8[8]; ld8(yd + row * 512 + c, y8); ld8(proj + row * NP + O_DZ + c, z8);
;                     const f32x4 b0 = *(const f32x4*)(gb + c), b1 = *(const f32x4*)(gb + c + 4);
; #pragma unroll
;                     for (int e = 0; e < 4; ++e) { o8[e] = y8[e] * sigmoidf_(acc[ai][bj][m][0][e] + b0[e]) * siluf_(z8[e]); o8[4 + e] = y8[4 + e] * sigmoidf_(acc[ai][bj][m][1][e] + b1[e]) * siluf_(z8[4 + e]); }
;                     st8(ys + row * DM + 1536 + c, o8); } }
	v_add_f32_e32 v39, v39, v231
	v_add_f32_e32 v40, v40, v232
	v_add_f32_e32 v41, v41, v233
	v_lshlrev_b32_e32 v146, 16, v150
	v_and_b32_e32 v149, 0xffff0000, v150
	v_lshlrev_b32_e32 v168, 16, v151
	v_and_b32_e32 v171, 0xffff0000, v151
	v_mul_f32_e32 v38, 0xbfb8aa3b, v38
	v_mul_f32_e32 v39, 0xbfb8aa3b, v39
	v_mul_f32_e32 v40, 0xbfb8aa3b, v40
	v_mul_f32_e32 v41, 0xbfb8aa3b, v41
	v_mul_f32_e32 v147, 0xbfb8aa3b, v146
	v_mul_f32_e32 v166, 0xbfb8aa3b, v149
	v_mul_f32_e32 v169, 0xbfb8aa3b, v168
	v_mul_f32_e32 v172, 0xbfb8aa3b, v171
	v_exp_f32_e32 v38, v38
	v_exp_f32_e32 v39, v39
	v_exp_f32_e32 v40, v40
	v_exp_f32_e32 v41, v41
	v_exp_f32_e32 v147, v147
	v_exp_f32_e32 v166, v166
	v_exp_f32_e32 v169, v169
	v_exp_f32_e32 v172, v172
	v_lshlrev_b32_e32 v148, 16, v212
	v_and_b32_e32 v167, 0xffff0000, v212
	v_lshlrev_b32_e32 v170, 16, v213
	v_and_b32_e32 v173, 0xffff0000, v213
	v_add_f32_e32 v38, 1.0, v38
	v_add_f32_e32 v39, 1.0, v39
	v_add_f32_e32 v40, 1.0, v40
	v_add_f32_e32 v41, 1.0, v41
	v_add_f32_e32 v147, 1.0, v147
	v_add_f32_e32 v166, 1.0, v166
	v_add_f32_e32 v169, 1.0, v169
	v_add_f32_e32 v172, 1.0, v172
	v_rcp_f32_e32 v38, v38
	v_rcp_f32_e32 v39, v39
	v_rcp_f32_e32 v40, v40
	v_rcp_f32_e32 v41, v41
	v_rcp_f32_e32 v147, v147
	v_rcp_f32_e32 v166, v166
	v_rcp_f32_e32 v169, v169
	v_rcp_f32_e32 v172, v172
	v_mul_f32_e32 v148, v38, v148
	v_mul_f32_e32 v167, v39, v167
	v_mul_f32_e32 v170, v40, v170
	v_mul_f32_e32 v173, v41, v173
	v_mul_f32_e32 v147, v147, v146
	v_mul_f32_e32 v166, v166, v149
	v_mul_f32_e32 v169, v169, v168
	v_mul_f32_e32 v172, v172, v171
	v_mul_f32_e32 v38, v147, v148
	v_mul_f32_e32 v39, v166, v167
	v_mul_f32_e32 v40, v169, v170
	v_mul_f32_e32 v41, v172, v173
	v_add_f32_e32 v34, v34, v234
	v_add_f32_e32 v35, v35, v235
	v_add_f32_e32 v36, v36, v236
	v_add_f32_e32 v37, v37, v237
	v_lshlrev_b32_e32 v146, 16, v152
	v_and_b32_e32 v149, 0xffff0000, v152
	v_lshlrev_b32_e32 v168, 16, v153
	v_and_b32_e32 v171, 0xffff0000, v153
	v_mul_f32_e32 v34, 0xbfb8aa3b, v34
	v_mul_f32_e32 v35, 0xbfb8aa3b, v35
	v_mul_f32_e32 v36, 0xbfb8aa3b, v36
	v_mul_f32_e32 v37, 0xbfb8aa3b, v37
	v_mul_f32_e32 v147, 0xbfb8aa3b, v146
	v_mul_f32_e32 v166, 0xbfb8aa3b, v149
	v_mul_f32_e32 v169, 0xbfb8aa3b, v168
	v_mul_f32_e32 v172, 0xbfb8aa3b, v171
	v_exp_f32_e32 v34, v34
	v_exp_f32_e32 v35, v35
	v_exp_f32_e32 v36, v36
	v_exp_f32_e32 v37, v37
	v_exp_f32_e32 v147, v147
	v_exp_f32_e32 v166, v166
	v_exp_f32_e32 v169, v169
	v_exp_f32_e32 v172, v172
	v_lshlrev_b32_e32 v148, 16, v214
	v_and_b32_e32 v167, 0xffff0000, v214
	v_lshlrev_b32_e32 v170, 16, v215
	v_and_b32_e32 v173, 0xffff0000, v215
	v_add_f32_e32 v34, 1.0, v34
	v_add_f32_e32 v35, 1.0, v35
	v_add_f32_e32 v36, 1.0, v36
	v_add_f32_e32 v37, 1.0, v37
	v_add_f32_e32 v147, 1.0, v147
	v_add_f32_e32 v166, 1.0, v166
	v_add_f32_e32 v169, 1.0, v169
	v_add_f32_e32 v172, 1.0, v172
	v_rcp_f32_e32 v34, v34
	v_rcp_f32_e32 v35, v35
	v_rcp_f32_e32 v36, v36
	v_rcp_f32_e32 v37, v37
	v_rcp_f32_e32 v147, v147
	v_rcp_f32_e32 v166, v166
	v_rcp_f32_e32 v169, v169
	v_rcp_f32_e32 v172, v172
	v_mul_f32_e32 v148, v34, v148
	v_mul_f32_e32 v167, v35, v167
	v_mul_f32_e32 v170, v36, v170
	v_mul_f32_e32 v173, v37, v173
	v_mul_f32_e32 v147, v147, v146
	v_mul_f32_e32 v166, v166, v149
	v_mul_f32_e32 v169, v169, v168
	v_mul_f32_e32 v172, v172, v171
	v_mul_f32_e32 v34, v147, v148
	v_mul_f32_e32 v35, v166, v167
	v_mul_f32_e32 v36, v169, v170
	v_mul_f32_e32 v37, v172, v173
	v_cvt_pk_bf16_f32 v212, v38, v39
	v_cvt_pk_bf16_f32 v213, v40, v41
	v_cvt_pk_bf16_f32 v214, v34, v35
	v_cvt_pk_bf16_f32 v215, v36, v37
	global_store_dwordx4 v[176:177], v[212:215], off offset:3328
	s_mov_b64 s[6:7], 0x10000
	v_lshl_add_u64 v[176:177], v[176:177], 0, s[6:7]
	s_waitcnt vmcnt(8)
	v_add_f32_e32 v30, v30, v222
	v_add_f32_e32 v31, v31, v223
	v_add_f32_e32 v32, v32, v224
	v_add_f32_e32 v33, v33, v225
	v_lshlrev_b32_e32 v146, 16, v138
	v_and_b32_e32 v149, 0xffff0000, v138
	v_lshlrev_b32_e32 v168, 16, v139
	v_and_b32_e32 v171, 0xffff0000, v139
	v_mul_f32_e32 v30, 0xbfb8aa3b, v30
	v_mul_f32_e32 v31, 0xbfb8aa3b, v31
	v_mul_f32_e32 v32, 0xbfb8aa3b, v32
	v_mul_f32_e32 v33, 0xbfb8aa3b, v33
	v_mul_f32_e32 v147, 0xbfb8aa3b, v146
	v_mul_f32_e32 v166, 0xbfb8aa3b, v149
	v_mul_f32_e32 v169, 0xbfb8aa3b, v168
	v_mul_f32_e32 v172, 0xbfb8aa3b, v171
	v_exp_f32_e32 v30, v30
	v_exp_f32_e32 v31, v31
	v_exp_f32_e32 v32, v32
	v_exp_f32_e32 v33, v33
	v_exp_f32_e32 v147, v147
	v_exp_f32_e32 v166, v166
	v_exp_f32_e32 v169, v169
	v_exp_f32_e32 v172, v172
	v_lshlrev_b32_e32 v148, 16, v130
	v_and_b32_e32 v167, 0xffff0000, v130
	v_lshlrev_b32_e32 v170, 16, v131
	v_and_b32_e32 v173, 0xffff0000, v131
	v_add_f32_e32 v30, 1.0, v30
	v_add_f32_e32 v31, 1.0, v31
	v_add_f32_e32 v32, 1.0, v32
	v_add_f32_e32 v33, 1.0, v33
	v_add_f32_e32 v147, 1.0, v147
	v_add_f32_e32 v166, 1.0, v166
	v_add_f32_e32 v169, 1.0, v169
	v_add_f32_e32 v172, 1.0, v172
	v_rcp_f32_e32 v30, v30
	v_rcp_f32_e32 v31, v31
	v_rcp_f32_e32 v32, v32
	v_rcp_f32_e32 v33, v33
	v_rcp_f32_e32 v147, v147
	v_rcp_f32_e32 v166, v166
	v_rcp_f32_e32 v169, v169
	v_rcp_f32_e32 v172, v172
	v_mul_f32_e32 v148, v30, v148
	v_mul_f32_e32 v167, v31, v167
	v_mul_f32_e32 v170, v32, v170
	v_mul_f32_e32 v173, v33, v173
	v_mul_f32_e32 v147, v147, v146
	v_mul_f32_e32 v166, v166, v149
	v_mul_f32_e32 v169, v169, v168
	v_mul_f32_e32 v172, v172, v171
	v_mul_f32_e32 v30, v147, v148
	v_mul_f32_e32 v31, v166, v167
	v_mul_f32_e32 v32, v169, v170
	v_mul_f32_e32 v33, v172, v173
	v_add_f32_e32 v26, v26, v226
	v_add_f32_e32 v27, v27, v227
	v_add_f32_e32 v28, v28, v228
	v_add_f32_e32 v29, v29, v229
	v_lshlrev_b32_e32 v146, 16, v140
	v_and_b32_e32 v149, 0xffff0000, v140
	v_lshlrev_b32_e32 v168, 16, v141
; __device__ __forceinline__ float sigmoidf_(float x) { return __builtin_amdgcn_rcpf(1.f + __expf(-x)); }
; __device__ __forceinline__ float siluf_(float x) { return x * sigmoidf_(x); }
;     __device__ __forceinline__ void operator()(AccT& acc, const Unit& u, int wr, int wc, int fr, int fq) const {
;     ...
;         for (int ai = 0; ai < 2; ++ai)
; #pragma unroll
;             for (int m = 0; m < 4; ++m) { const size_t row = (size_t)(row0 + ai * 128 + m * 16);
; #pragma unroll
;                 for (int bj = 0; bj < 2; ++bj) { const int c = col0 + bj * 128;
;                     float y8[8], z8[8], o8[8]; ld8(yd + row * 512 + c, y8); ld8(proj + row * NP + O_DZ + c, z8);
;                     const f32x4 b0 = *(const f32x4*)(gb + c), b1 = *(const f32x4*)(gb + c + 4);
; #pragma unroll
;                     for (int e = 0; e < 4; ++e) { o8[e] = y8[e] * sigmoidf_(acc[ai][bj][m][0][e] + b0[e]) * siluf_(z8[e]); o8[4 + e] = y8[4 + e] * sigmoidf_(acc[ai][bj][m][1][e] + b1[e]) * siluf_(z8[4 + e]); }
;                     st8(ys + row * DM + 1536 + c, o8); } }
	v_and_b32_e32 v171, 0xffff0000, v141
	v_mul_f32_e32 v26, 0xbfb8aa3b, v26
	v_mul_f32_e32 v27, 0xbfb8aa3b, v27
	v_mul_f32_e32 v28, 0xbfb8aa3b, v28
	v_mul_f32_e32 v29, 0xbfb8aa3b, v29
	v_mul_f32_e32 v147, 0xbfb8aa3b, v146
	v_mul_f32_e32 v166, 0xbfb8aa3b, v149
	v_mul_f32_e32 v169, 0xbfb8aa3b, v168
	v_mul_f32_e32 v172, 0xbfb8aa3b, v171
	v_exp_f32_e32 v26, v26
	v_exp_f32_e32 v27, v27
	v_exp_f32_e32 v28, v28
	v_exp_f32_e32 v29, v29
	v_exp_f32_e32 v147, v147
	v_exp_f32_e32 v166, v166
	v_exp_f32_e32 v169, v169
	v_exp_f32_e32 v172, v172
	v_lshlrev_b32_e32 v148, 16, v132
	v_and_b32_e32 v167, 0xffff0000, v132
	v_lshlrev_b32_e32 v170, 16, v133
	v_and_b32_e32 v173, 0xffff0000, v133
	v_add_f32_e32 v26, 1.0, v26
	v_add_f32_e32 v27, 1.0, v27
	v_add_f32_e32 v28, 1.0, v28
	v_add_f32_e32 v29, 1.0, v29
	v_add_f32_e32 v147, 1.0, v147
	v_add_f32_e32 v166, 1.0, v166
	v_add_f32_e32 v169, 1.0, v169
	v_add_f32_e32 v172, 1.0, v172
	v_rcp_f32_e32 v26, v26
	v_rcp_f32_e32 v27, v27
	v_rcp_f32_e32 v28, v28
	v_rcp_f32_e32 v29, v29
	v_rcp_f32_e32 v147, v147
	v_rcp_f32_e32 v166, v166
	v_rcp_f32_e32 v169, v169
	v_rcp_f32_e32 v172, v172
	v_mul_f32_e32 v148, v26, v148
	v_mul_f32_e32 v167, v27, v167
	v_mul_f32_e32 v170, v28, v170
	v_mul_f32_e32 v173, v29, v173
	v_mul_f32_e32 v147, v147, v146
	v_mul_f32_e32 v166, v166, v149
	v_mul_f32_e32 v169, v169, v168
	v_mul_f32_e32 v172, v172, v171
	v_mul_f32_e32 v26, v147, v148
	v_mul_f32_e32 v27, v166, v167
	v_mul_f32_e32 v28, v169, v170
	v_mul_f32_e32 v29, v172, v173
	v_cvt_pk_bf16_f32 v130, v30, v31
	v_cvt_pk_bf16_f32 v131, v32, v33
	v_cvt_pk_bf16_f32 v132, v26, v27
	v_cvt_pk_bf16_f32 v133, v28, v29
	global_store_dwordx4 v[176:177], v[130:133], off offset:3072
	v_add_f32_e32 v22, v22, v230
	v_add_f32_e32 v23, v23, v231
	v_add_f32_e32 v24, v24, v232
	v_add_f32_e32 v25, v25, v233
	v_lshlrev_b32_e32 v146, 16, v142
	v_and_b32_e32 v149, 0xffff0000, v142
	v_lshlrev_b32_e32 v168, 16, v143
	v_and_b32_e32 v171, 0xffff0000, v143
	v_mul_f32_e32 v22, 0xbfb8aa3b, v22
	v_mul_f32_e32 v23, 0xbfb8aa3b, v23
	v_mul_f32_e32 v24, 0xbfb8aa3b, v24
	v_mul_f32_e32 v25, 0xbfb8aa3b, v25
	v_mul_f32_e32 v147, 0xbfb8aa3b, v146
	v_mul_f32_e32 v166, 0xbfb8aa3b, v149
	v_mul_f32_e32 v169, 0xbfb8aa3b, v168
	v_mul_f32_e32 v172, 0xbfb8aa3b, v171
	v_exp_f32_e32 v22, v22
	v_exp_f32_e32 v23, v23
	v_exp_f32_e32 v24, v24
	v_exp_f32_e32 v25, v25
	v_exp_f32_e32 v147, v147
	v_exp_f32_e32 v166, v166
	v_exp_f32_e32 v169, v169
	v_exp_f32_e32 v172, v172
	v_lshlrev_b32_e32 v148, 16, v134
	v_and_b32_e32 v167, 0xffff0000, v134
	v_lshlrev_b32_e32 v170, 16, v135
	v_and_b32_e32 v173, 0xffff0000, v135
	v_add_f32_e32 v22, 1.0, v22
	v_add_f32_e32 v23, 1.0, v23
	v_add_f32_e32 v24, 1.0, v24
	v_add_f32_e32 v25, 1.0, v25
	v_add_f32_e32 v147, 1.0, v147
	v_add_f32_e32 v166, 1.0, v166
	v_add_f32_e32 v169, 1.0, v169
	v_add_f32_e32 v172, 1.0, v172
	v_rcp_f32_e32 v22, v22
	v_rcp_f32_e32 v23, v23
	v_rcp_f32_e32 v24, v24
	v_rcp_f32_e32 v25, v25
	v_rcp_f32_e32 v147, v147
	v_rcp_f32_e32 v166, v166
	v_rcp_f32_e32 v169, v169
	v_rcp_f32_e32 v172, v172
	v_mul_f32_e32 v148, v22, v148
	v_mul_f32_e32 v167, v23, v167
	v_mul_f32_e32 v170, v24, v170
	v_mul_f32_e32 v173, v25, v173
	v_mul_f32_e32 v147, v147, v146
	v_mul_f32_e32 v166, v166, v149
	v_mul_f32_e32 v169, v169, v168
	v_mul_f32_e32 v172, v172, v171
	v_mul_f32_e32 v22, v147, v148
	v_mul_f32_e32 v23, v166, v167
	v_mul_f32_e32 v24, v169, v170
	v_mul_f32_e32 v25, v172, v173
	v_add_f32_e32 v18, v18, v234
	v_add_f32_e32 v19, v19, v235
	v_add_f32_e32 v20, v20, v236
	v_add_f32_e32 v21, v21, v237
	v_lshlrev_b32_e32 v146, 16, v144
	v_and_b32_e32 v149, 0xffff0000, v144
	v_lshlrev_b32_e32 v168, 16, v145
	v_and_b32_e32 v171, 0xffff0000, v145
	v_mul_f32_e32 v18, 0xbfb8aa3b, v18
	v_mul_f32_e32 v19, 0xbfb8aa3b, v19
	v_mul_f32_e32 v20, 0xbfb8aa3b, v20
	v_mul_f32_e32 v21, 0xbfb8aa3b, v21
	v_mul_f32_e32 v147, 0xbfb8aa3b, v146
	v_mul_f32_e32 v166, 0xbfb8aa3b, v149
	v_mul_f32_e32 v169, 0xbfb8aa3b, v168
	v_mul_f32_e32 v172, 0xbfb8aa3b, v171
	v_exp_f32_e32 v18, v18
	v_exp_f32_e32 v19, v19
	v_exp_f32_e32 v20, v20
	v_exp_f32_e32 v21, v21
	v_exp_f32_e32 v147, v147
	v_exp_f32_e32 v166, v166
	v_exp_f32_e32 v169, v169
	v_exp_f32_e32 v172, v172
	v_lshlrev_b32_e32 v148, 16, v136
	v_and_b32_e32 v167, 0xffff0000, v136
	v_lshlrev_b32_e32 v170, 16, v137
	v_and_b32_e32 v173, 0xffff0000, v137
	v_add_f32_e32 v18, 1.0, v18
	v_add_f32_e32 v19, 1.0, v19
	v_add_f32_e32 v20, 1.0, v20
	v_add_f32_e32 v21, 1.0, v21
	v_add_f32_e32 v147, 1.0, v147
	v_add_f32_e32 v166, 1.0, v166
	v_add_f32_e32 v169, 1.0, v169
	v_add_f32_e32 v172, 1.0, v172
	v_rcp_f32_e32 v18, v18
	v_rcp_f32_e32 v19, v19
	v_rcp_f32_e32 v20, v20
	v_rcp_f32_e32 v21, v21
	v_rcp_f32_e32 v147, v147
	v_rcp_f32_e32 v166, v166
	v_rcp_f32_e32 v169, v169
	v_rcp_f32_e32 v172, v172
	v_mul_f32_e32 v148, v18, v148
	v_mul_f32_e32 v167, v19, v167
	v_mul_f32_e32 v170, v20, v170
	v_mul_f32_e32 v173, v21, v173
	v_mul_f32_e32 v147, v147, v146
	v_mul_f32_e32 v166, v166, v149
	v_mul_f32_e32 v169, v169, v168
	v_mul_f32_e32 v172, v172, v171
	v_mul_f32_e32 v18, v147, v148
	v_mul_f32_e32 v19, v166, v167
	v_mul_f32_e32 v20, v169, v170
	v_mul_f32_e32 v21, v172, v173
	v_cvt_pk_bf16_f32 v134, v22, v23
	v_cvt_pk_bf16_f32 v135, v24, v25
	v_cvt_pk_bf16_f32 v136, v18, v19
	v_cvt_pk_bf16_f32 v137, v20, v21
	global_store_dwordx4 v[176:177], v[134:137], off offset:3328
	s_mov_b64 s[6:7], 0x10000
	v_lshl_add_u64 v[176:177], v[176:177], 0, s[6:7]
	s_waitcnt vmcnt(4)
; __device__ __forceinline__ float sigmoidf_(float x) { return __builtin_amdgcn_rcpf(1.f + __expf(-x)); }
; __device__ __forceinline__ float siluf_(float x) { return x * sigmoidf_(x); }
;     __device__ __forceinline__ void operator()(AccT& acc, const Unit& u, int wr, int wc, int fr, int fq) const {
;     ...
;         for (int ai = 0; ai < 2; ++ai)
; #pragma unroll
;             for (int m = 0; m < 4; ++m) { const size_t row = (size_t)(row0 + ai * 128 + m * 16);
; #pragma unroll
;                 for (int bj = 0; bj < 2; ++bj) { const int c = col0 + bj * 128;
;                     float y8[8], z8[8], o8[8]; ld8(yd + row * 512 + c, y8); ld8(proj + row * NP + O_DZ + c, z8);
;                     const f32x4 b0 = *(const f32x4*)(gb + c), b1 = *(const f32x4*)(gb + c + 4);
; #pragma unroll
;                     for (int e = 0; e < 4; ++e) { o8[e] = y8[e] * sigmoidf_(acc[ai][bj][m][0][e] + b0[e]) * siluf_(z8[e]); o8[4 + e] = y8[4 + e] * sigmoidf_(acc[ai][bj][m][1][e] + b1[e]) * siluf_(z8[4 + e]); }
;                     st8(ys + row * DM + 1536 + c, o8); } }
	v_add_f32_e32 v14, v14, v222
	v_add_f32_e32 v15, v15, v223
	v_add_f32_e32 v16, v16, v224
	v_add_f32_e32 v17, v17, v225
	v_lshlrev_b32_e32 v146, 16, v196
	v_and_b32_e32 v149, 0xffff0000, v196
	v_lshlrev_b32_e32 v168, 16, v197
	v_and_b32_e32 v171, 0xffff0000, v197
	v_mul_f32_e32 v14, 0xbfb8aa3b, v14
	v_mul_f32_e32 v15, 0xbfb8aa3b, v15
	v_mul_f32_e32 v16, 0xbfb8aa3b, v16
	v_mul_f32_e32 v17, 0xbfb8aa3b, v17
	v_mul_f32_e32 v147, 0xbfb8aa3b, v146
	v_mul_f32_e32 v166, 0xbfb8aa3b, v149
	v_mul_f32_e32 v169, 0xbfb8aa3b, v168
	v_mul_f32_e32 v172, 0xbfb8aa3b, v171
	v_exp_f32_e32 v14, v14
	v_exp_f32_e32 v15, v15
	v_exp_f32_e32 v16, v16
	v_exp_f32_e32 v17, v17
	v_exp_f32_e32 v147, v147
	v_exp_f32_e32 v166, v166
	v_exp_f32_e32 v169, v169
	v_exp_f32_e32 v172, v172
	v_lshlrev_b32_e32 v148, 16, v188
	v_and_b32_e32 v167, 0xffff0000, v188
	v_lshlrev_b32_e32 v170, 16, v189
	v_and_b32_e32 v173, 0xffff0000, v189
	v_add_f32_e32 v14, 1.0, v14
	v_add_f32_e32 v15, 1.0, v15
	v_add_f32_e32 v16, 1.0, v16
	v_add_f32_e32 v17, 1.0, v17
	v_add_f32_e32 v147, 1.0, v147
	v_add_f32_e32 v166, 1.0, v166
	v_add_f32_e32 v169, 1.0, v169
	v_add_f32_e32 v172, 1.0, v172
	v_rcp_f32_e32 v14, v14
	v_rcp_f32_e32 v15, v15
	v_rcp_f32_e32 v16, v16
	v_rcp_f32_e32 v17, v17
	v_rcp_f32_e32 v147, v147
	v_rcp_f32_e32 v166, v166
	v_rcp_f32_e32 v169, v169
	v_rcp_f32_e32 v172, v172
	v_mul_f32_e32 v148, v14, v148
	v_mul_f32_e32 v167, v15, v167
	v_mul_f32_e32 v170, v16, v170
	v_mul_f32_e32 v173, v17, v173
	v_mul_f32_e32 v147, v147, v146
	v_mul_f32_e32 v166, v166, v149
	v_mul_f32_e32 v169, v169, v168
	v_mul_f32_e32 v172, v172, v171
	v_mul_f32_e32 v14, v147, v148
	v_mul_f32_e32 v15, v166, v167
	v_mul_f32_e32 v16, v169, v170
	v_mul_f32_e32 v17, v172, v173
	v_add_f32_e32 v10, v10, v226
	v_add_f32_e32 v11, v11, v227
	v_add_f32_e32 v12, v12, v228
	v_add_f32_e32 v13, v13, v229
	v_lshlrev_b32_e32 v146, 16, v198
	v_and_b32_e32 v149, 0xffff0000, v198
	v_lshlrev_b32_e32 v168, 16, v199
	v_and_b32_e32 v171, 0xffff0000, v199
	v_mul_f32_e32 v10, 0xbfb8aa3b, v10
	v_mul_f32_e32 v11, 0xbfb8aa3b, v11
	v_mul_f32_e32 v12, 0xbfb8aa3b, v12
	v_mul_f32_e32 v13, 0xbfb8aa3b, v13
	v_mul_f32_e32 v147, 0xbfb8aa3b, v146
	v_mul_f32_e32 v166, 0xbfb8aa3b, v149
	v_mul_f32_e32 v169, 0xbfb8aa3b, v168
	v_mul_f32_e32 v172, 0xbfb8aa3b, v171
	v_exp_f32_e32 v10, v10
	v_exp_f32_e32 v11, v11
	v_exp_f32_e32 v12, v12
	v_exp_f32_e32 v13, v13
	v_exp_f32_e32 v147, v147
	v_exp_f32_e32 v166, v166
	v_exp_f32_e32 v169, v169
	v_exp_f32_e32 v172, v172
	v_lshlrev_b32_e32 v148, 16, v190
	v_and_b32_e32 v167, 0xffff0000, v190
	v_lshlrev_b32_e32 v170, 16, v191
	v_and_b32_e32 v173, 0xffff0000, v191
	v_add_f32_e32 v10, 1.0, v10
	v_add_f32_e32 v11, 1.0, v11
	v_add_f32_e32 v12, 1.0, v12
	v_add_f32_e32 v13, 1.0, v13
	v_add_f32_e32 v147, 1.0, v147
	v_add_f32_e32 v166, 1.0, v166
	v_add_f32_e32 v169, 1.0, v169
	v_add_f32_e32 v172, 1.0, v172
	v_rcp_f32_e32 v10, v10
	v_rcp_f32_e32 v11, v11
	v_rcp_f32_e32 v12, v12
	v_rcp_f32_e32 v13, v13
	v_rcp_f32_e32 v147, v147
	v_rcp_f32_e32 v166, v166
	v_rcp_f32_e32 v169, v169
	v_rcp_f32_e32 v172, v172
	v_mul_f32_e32 v148, v10, v148
	v_mul_f32_e32 v167, v11, v167
	v_mul_f32_e32 v170, v12, v170
	v_mul_f32_e32 v173, v13, v173
	v_mul_f32_e32 v147, v147, v146
	v_mul_f32_e32 v166, v166, v149
	v_mul_f32_e32 v169, v169, v168
	v_mul_f32_e32 v172, v172, v171
	v_mul_f32_e32 v10, v147, v148
	v_mul_f32_e32 v11, v166, v167
	v_mul_f32_e32 v12, v169, v170
	v_mul_f32_e32 v13, v172, v173
	v_cvt_pk_bf16_f32 v188, v14, v15
	v_cvt_pk_bf16_f32 v189, v16, v17
	v_cvt_pk_bf16_f32 v190, v10, v11
	v_cvt_pk_bf16_f32 v191, v12, v13
	global_store_dwordx4 v[176:177], v[188:191], off offset:3072
	v_add_f32_e32 v6, v6, v230
	v_add_f32_e32 v7, v7, v231
	v_add_f32_e32 v8, v8, v232
	v_add_f32_e32 v9, v9, v233
	v_lshlrev_b32_e32 v146, 16, v200
; __device__ __forceinline__ float sigmoidf_(float x) { return __builtin_amdgcn_rcpf(1.f + __expf(-x)); }
; __device__ __forceinline__ float siluf_(float x) { return x * sigmoidf_(x); }
; __device__ __forceinline__ int fresh_tid() { int t = threadIdx.x; asm volatile("" : "+v"(t)); return t; }
; template <class Epi>
; __device__ __forceinline__ void gemm_phase(LAS unsigned char* lds, const Gemm g, const StaticOrder& S, const Epi& E) {
;     ...
;         { const int t2 = fresh_tid(); const int w2 = __builtin_amdgcn_readfirstlane(t2 >> 6); E(acc, cur, w2 >> 2, w2 & 3, t2 & 15, (t2 >> 4) & 3); }
;         if (!has_next) break;
; #pragma unroll
;         for (int a = 0; a < 2; ++a)
; #pragma unroll
;             for (int b = 0; b < 2; ++b)
; #pragma unroll
;                 for (int m = 0; m < 4; ++m)
; #pragma unroll
;                     for (int n = 0; n < 2; ++n) acc[a][b][m][n] = (f32x4){0.f, 0.f, 0.f, 0.f};
;         cur = nxt; cA = nA; cB = nB; ++ui;
;     __device__ __forceinline__ void operator()(AccT& acc, const Unit& u, int wr, int wc, int fr, int fq) const {
;     ...
;         for (int ai = 0; ai < 2; ++ai)
; #pragma unroll
;             for (int m = 0; m < 4; ++m) { const size_t row = (size_t)(row0 + ai * 128 + m * 16);
; #pragma unroll
;                 for (int bj = 0; bj < 2; ++bj) { const int c = col0 + bj * 128;
;                     float y8[8], z8[8], o8[8]; ld8(yd + row * 512 + c, y8); ld8(proj + row * NP + O_DZ + c, z8);
;                     const f32x4 b0 = *(const f32x4*)(gb + c), b1 = *(const f32x4*)(gb + c + 4);
; #pragma unroll
;                     for (int e = 0; e < 4; ++e) { o8[e] = y8[e] * sigmoidf_(acc[ai][bj][m][0][e] + b0[e]) * siluf_(z8[e]); o8[4 + e] = y8[4 + e] * sigmoidf_(acc[ai][bj][m][1][e] + b1[e]) * siluf_(z8[4 + e]); }
;                     st8(ys + row * DM + 1536 + c, o8); } }
	v_and_b32_e32 v149, 0xffff0000, v200
	v_lshlrev_b32_e32 v168, 16, v201
	v_and_b32_e32 v171, 0xffff0000, v201
	v_mul_f32_e32 v6, 0xbfb8aa3b, v6
	v_mul_f32_e32 v7, 0xbfb8aa3b, v7
	v_mul_f32_e32 v8, 0xbfb8aa3b, v8
	v_mul_f32_e32 v9, 0xbfb8aa3b, v9
	v_mul_f32_e32 v147, 0xbfb8aa3b, v146
	v_mul_f32_e32 v166, 0xbfb8aa3b, v149
	v_mul_f32_e32 v169, 0xbfb8aa3b, v168
	v_mul_f32_e32 v172, 0xbfb8aa3b, v171
	v_exp_f32_e32 v6, v6
	v_exp_f32_e32 v7, v7
	v_exp_f32_e32 v8, v8
	v_exp_f32_e32 v9, v9
	v_exp_f32_e32 v147, v147
	v_exp_f32_e32 v166, v166
	v_exp_f32_e32 v169, v169
	v_exp_f32_e32 v172, v172
	v_lshlrev_b32_e32 v148, 16, v192
	v_and_b32_e32 v167, 0xffff0000, v192
	v_lshlrev_b32_e32 v170, 16, v193
	v_and_b32_e32 v173, 0xffff0000, v193
	v_add_f32_e32 v6, 1.0, v6
	v_add_f32_e32 v7, 1.0, v7
	v_add_f32_e32 v8, 1.0, v8
	v_add_f32_e32 v9, 1.0, v9
	v_add_f32_e32 v147, 1.0, v147
	v_add_f32_e32 v166, 1.0, v166
	v_add_f32_e32 v169, 1.0, v169
	v_add_f32_e32 v172, 1.0, v172
	v_rcp_f32_e32 v6, v6
	v_rcp_f32_e32 v7, v7
	v_rcp_f32_e32 v8, v8
	v_rcp_f32_e32 v9, v9
	v_rcp_f32_e32 v147, v147
	v_rcp_f32_e32 v166, v166
	v_rcp_f32_e32 v169, v169
	v_rcp_f32_e32 v172, v172
	v_mul_f32_e32 v148, v6, v148
	v_mul_f32_e32 v167, v7, v167
	v_mul_f32_e32 v170, v8, v170
	v_mul_f32_e32 v173, v9, v173
	v_mul_f32_e32 v147, v147, v146
	v_mul_f32_e32 v166, v166, v149
	v_mul_f32_e32 v169, v169, v168
	v_mul_f32_e32 v172, v172, v171
	v_mul_f32_e32 v6, v147, v148
	v_mul_f32_e32 v7, v166, v167
	v_mul_f32_e32 v8, v169, v170
	v_mul_f32_e32 v9, v172, v173
	v_add_f32_e32 v2, v2, v234
	v_add_f32_e32 v3, v3, v235
	v_add_f32_e32 v4, v4, v236
	v_add_f32_e32 v5, v5, v237
	v_lshlrev_b32_e32 v146, 16, v202
	v_and_b32_e32 v149, 0xffff0000, v202
	v_lshlrev_b32_e32 v168, 16, v203
	v_and_b32_e32 v171, 0xffff0000, v203
	v_mul_f32_e32 v2, 0xbfb8aa3b, v2
	v_mul_f32_e32 v3, 0xbfb8aa3b, v3
	v_mul_f32_e32 v4, 0xbfb8aa3b, v4
	v_mul_f32_e32 v5, 0xbfb8aa3b, v5
	v_mul_f32_e32 v147, 0xbfb8aa3b, v146
	v_mul_f32_e32 v166, 0xbfb8aa3b, v149
	v_mul_f32_e32 v169, 0xbfb8aa3b, v168
	v_mul_f32_e32 v172, 0xbfb8aa3b, v171
	v_exp_f32_e32 v2, v2
	v_exp_f32_e32 v3, v3
	v_exp_f32_e32 v4, v4
	v_exp_f32_e32 v5, v5
	v_exp_f32_e32 v147, v147
	v_exp_f32_e32 v166, v166
	v_exp_f32_e32 v169, v169
	v_exp_f32_e32 v172, v172
	v_lshlrev_b32_e32 v148, 16, v194
	v_and_b32_e32 v167, 0xffff0000, v194
	v_lshlrev_b32_e32 v170, 16, v195
	v_and_b32_e32 v173, 0xffff0000, v195
	v_add_f32_e32 v2, 1.0, v2
	v_add_f32_e32 v3, 1.0, v3
	v_add_f32_e32 v4, 1.0, v4
	v_add_f32_e32 v5, 1.0, v5
	v_add_f32_e32 v147, 1.0, v147
	v_add_f32_e32 v166, 1.0, v166
	v_add_f32_e32 v169, 1.0, v169
	v_add_f32_e32 v172, 1.0, v172
	v_rcp_f32_e32 v2, v2
	v_rcp_f32_e32 v3, v3
	v_rcp_f32_e32 v4, v4
	v_rcp_f32_e32 v5, v5
	v_rcp_f32_e32 v147, v147
	v_rcp_f32_e32 v166, v166
	v_rcp_f32_e32 v169, v169
	v_rcp_f32_e32 v172, v172
	v_mul_f32_e32 v148, v2, v148
	v_mul_f32_e32 v167, v3, v167
	v_mul_f32_e32 v170, v4, v170
	v_mul_f32_e32 v173, v5, v173
	v_mul_f32_e32 v147, v147, v146
	v_mul_f32_e32 v166, v166, v149
	v_mul_f32_e32 v169, v169, v168
	v_mul_f32_e32 v172, v172, v171
	v_mul_f32_e32 v2, v147, v148
	v_mul_f32_e32 v3, v166, v167
	v_mul_f32_e32 v4, v169, v170
	v_mul_f32_e32 v5, v172, v173
	v_cvt_pk_bf16_f32 v192, v6, v7
	v_cvt_pk_bf16_f32 v193, v8, v9
	v_cvt_pk_bf16_f32 v194, v2, v3
	v_cvt_pk_bf16_f32 v195, v4, v5
	global_store_dwordx4 v[176:177], v[192:195], off offset:3328
	s_mov_b64 s[6:7], s[62:63]
	s_mov_b64 s[20:21], s[66:67]
	s_and_b64 vcc, exec, s[50:51]
	s_cbranch_vccz .LBB0_1295
	s_waitcnt vmcnt(0)
	v_readlane_b32 s52, v255, 42
	v_readlane_b32 s82, v255, 50
	s_cmpk_gt_u32 s23, 0xff
	v_readlane_b32 s51, v255, 41
	v_readlane_b32 s53, v255, 43
	s_mov_b32 s86, 0x3fb8aa3b
	v_readlane_b32 s83, v255, 51
	s_cbranch_scc1 .LBB0_1306
	s_barrier
